# v49 + layer-1 attention epilogue: 32 serialized gate loads (ushort + vmcnt(0) each) hoisted to loop top into spare VGPRs, counted waits
# speedup vs baseline: 1.0083x; 1.0083x over previous
; #define LAS __attribute__((address_space(3)))
; __device__ __forceinline__ float bf2f(bf16_t b) { return __uint_as_float(((unsigned)b) << 16); }
; __device__ __forceinline__ float siluf_(float x) { return x * frcp(1.0f + __expf(-x)); }
; __device__ __forceinline__ f32x4 mfma16(bf16x8 a, bf16x8 b, f32x4 c) { return __builtin_amdgcn_mfma_f32_16x16x32_bf16(a, b, c, 0, 0, 0); }
; __device__ __forceinline__ void attn_item(const P& p, const Ctx& c, int layer, int it, const bf16_t* Qp, int ldq, bf16_t* YM, int ldy, const bf16_t* Zp, int ldz) {
;     ...
;         const int row0 = b * SEGT + qb * 256 + c.wv * 32 + pass * 16;
;         bf16x8 qf[4];
; #pragma unroll
;         for (int kk = 0; kk < 4; ++kk) qf[kk] = *(const bf16x8*)(Qp + (size_t)(row0 + l15) * ldq + head * 128 + kk * 32 + quad * 8);
;         f32x4 acc[16];
; #pragma unroll
;         for (int mt = 0; mt < 16; ++mt) { acc[mt] = (f32x4){0.f, 0.f, 0.f, 0.f};
; #pragma unroll
;             for (int kk = 0; kk < 4; ++kk) { const bf16x8 a = *(const LAS bf16x8*)(Ks + (mt * 16 + l15) * 136 + kk * 32 + quad * 8); acc[mt] = mfma16(a, qf[kk], acc[mt]); }
;     ...
;             for (int j = 0; j < 4; ++j) { const size_t rr = (size_t)(row0 + quad * 4 + j); const int cc = head * 128 + nt * 16 + l15; float ov = o[nt][j];
;                 if (Zp) ov *= siluf_(bf2f(Zp[rr * ldz + cc]));
.LBB0_826:
	s_or_b32 s11, s10, s11
	v_or_b32_e32 v6, s11, v110
	v_mad_i64_i32 v[6:7], s[12:13], v6, s44, v[2:3]
	global_load_dwordx4 v[78:81], v[6:7], off
	global_load_dwordx4 v[74:77], v[6:7], off offset:64
	global_load_dwordx4 v[70:73], v[6:7], off offset:128
	s_nop 0
	global_load_dwordx4 v[6:9], v[6:7], off offset:192
	ds_read_b128 v[10:13], v113
	ds_read_b128 v[14:17], v113 offset:64
	s_waitcnt vmcnt(3) lgkmcnt(1)
	v_mfma_f32_16x16x32_bf16 v[10:13], v[10:13], v[78:81], 0
	s_waitcnt vmcnt(2) lgkmcnt(0)
	v_mfma_f32_16x16x32_bf16 v[10:13], v[14:17], v[74:77], v[10:13]
	ds_read_b128 v[14:17], v113 offset:128
	s_waitcnt vmcnt(1) lgkmcnt(0)
	v_mfma_f32_16x16x32_bf16 v[10:13], v[14:17], v[70:73], v[10:13]
	ds_read_b128 v[14:17], v113 offset:192
	s_waitcnt vmcnt(0) lgkmcnt(0)
	v_mfma_f32_16x16x32_bf16 v[66:69], v[14:17], v[6:9], v[10:13]
	v_or_b32_e32 v180, s11, v112
	v_or_b32_e32 v181, 1, v180
	v_or_b32_e32 v182, 2, v180
	v_or_b32_e32 v183, 3, v180
	v_mov_b64_e32 v[184:185], s[4:5]
	v_mov_b32_e32 v200, v86
	v_mov_b32_e32 v201, v5
	v_mov_b32_e32 v202, v88
	v_mov_b32_e32 v203, v5
	v_mov_b32_e32 v204, v90
	v_mov_b32_e32 v205, v5
	v_mov_b32_e32 v206, v92
	v_mov_b32_e32 v207, v5
	v_mov_b32_e32 v208, v94
	v_mov_b32_e32 v209, v5
	v_mov_b32_e32 v210, v96
	v_mov_b32_e32 v211, v5
	v_mad_i64_i32 v[186:187], s[12:13], v180, s44, v[84:85]
	global_load_ushort v124, v[186:187], off
	v_mad_i64_i32 v[188:189], s[12:13], v181, s44, v[84:85]
	global_load_ushort v125, v[188:189], off
	v_mad_i64_i32 v[186:187], s[12:13], v182, s44, v[84:85]
	global_load_ushort v126, v[186:187], off
	v_mad_i64_i32 v[188:189], s[12:13], v183, s44, v[84:85]
	global_load_ushort v127, v[188:189], off
	v_mad_i64_i32 v[190:191], s[12:13], v180, s44, v[184:185]
	v_mad_i64_i32 v[192:193], s[12:13], v181, s44, v[184:185]
	v_mad_i64_i32 v[194:195], s[12:13], v182, s44, v[184:185]
	v_mad_i64_i32 v[196:197], s[12:13], v183, s44, v[184:185]
	v_lshl_add_u64 v[186:187], v[190:191], 0, v[4:5]
	global_load_ushort v128, v[186:187], off
	v_lshl_add_u64 v[188:189], v[192:193], 0, v[4:5]
	global_load_ushort v129, v[188:189], off
	v_lshl_add_u64 v[186:187], v[194:195], 0, v[4:5]
	global_load_ushort v130, v[186:187], off
	v_lshl_add_u64 v[188:189], v[196:197], 0, v[4:5]
	global_load_ushort v131, v[188:189], off
	v_lshl_add_u64 v[186:187], v[190:191], 0, v[200:201]
	global_load_ushort v132, v[186:187], off
	v_lshl_add_u64 v[188:189], v[192:193], 0, v[200:201]
	global_load_ushort v133, v[188:189], off
	v_lshl_add_u64 v[186:187], v[194:195], 0, v[200:201]
	global_load_ushort v134, v[186:187], off
	v_lshl_add_u64 v[188:189], v[196:197], 0, v[200:201]
	global_load_ushort v135, v[188:189], off
	v_lshl_add_u64 v[186:187], v[190:191], 0, v[202:203]
	global_load_ushort v136, v[186:187], off
	v_lshl_add_u64 v[188:189], v[192:193], 0, v[202:203]
	global_load_ushort v137, v[188:189], off
	v_lshl_add_u64 v[186:187], v[194:195], 0, v[202:203]
	global_load_ushort v138, v[186:187], off
	v_lshl_add_u64 v[188:189], v[196:197], 0, v[202:203]
	global_load_ushort v139, v[188:189], off
	v_lshl_add_u64 v[186:187], v[190:191], 0, v[204:205]
	global_load_ushort v140, v[186:187], off
	v_lshl_add_u64 v[188:189], v[192:193], 0, v[204:205]
	global_load_ushort v141, v[188:189], off
	v_lshl_add_u64 v[186:187], v[194:195], 0, v[204:205]
	global_load_ushort v142, v[186:187], off
	v_lshl_add_u64 v[188:189], v[196:197], 0, v[204:205]
	global_load_ushort v143, v[188:189], off
	v_lshl_add_u64 v[186:187], v[190:191], 0, v[206:207]
	global_load_ushort v144, v[186:187], off
	v_lshl_add_u64 v[188:189], v[192:193], 0, v[206:207]
	global_load_ushort v145, v[188:189], off
	v_lshl_add_u64 v[186:187], v[194:195], 0, v[206:207]
	global_load_ushort v146, v[186:187], off
	v_lshl_add_u64 v[188:189], v[196:197], 0, v[206:207]
	global_load_ushort v147, v[188:189], off
	v_lshl_add_u64 v[186:187], v[190:191], 0, v[208:209]
	global_load_ushort v148, v[186:187], off
	v_lshl_add_u64 v[188:189], v[192:193], 0, v[208:209]
	global_load_ushort v149, v[188:189], off
	v_lshl_add_u64 v[186:187], v[194:195], 0, v[208:209]
	global_load_ushort v150, v[186:187], off
	v_lshl_add_u64 v[188:189], v[196:197], 0, v[208:209]
	global_load_ushort v151, v[188:189], off
	v_lshl_add_u64 v[186:187], v[190:191], 0, v[210:211]
	global_load_ushort v152, v[186:187], off
	v_lshl_add_u64 v[188:189], v[192:193], 0, v[210:211]
	global_load_ushort v153, v[188:189], off
	v_lshl_add_u64 v[186:187], v[194:195], 0, v[210:211]
	global_load_ushort v154, v[186:187], off
	v_lshl_add_u64 v[188:189], v[196:197], 0, v[210:211]
	global_load_ushort v155, v[188:189], off
	s_nop 4
	ds_read_b128 v[10:13], v113 offset:4352
	ds_read_b128 v[14:17], v113 offset:4416
	s_waitcnt lgkmcnt(1)
	v_mfma_f32_16x16x32_bf16 v[10:13], v[10:13], v[78:81], 0
	s_waitcnt lgkmcnt(0)
	v_mfma_f32_16x16x32_bf16 v[10:13], v[14:17], v[74:77], v[10:13]
	ds_read_b128 v[14:17], v113 offset:4480
	s_waitcnt lgkmcnt(0)
	v_mfma_f32_16x16x32_bf16 v[10:13], v[14:17], v[70:73], v[10:13]
	ds_read_b128 v[14:17], v113 offset:4544
	s_waitcnt lgkmcnt(0)
	v_mfma_f32_16x16x32_bf16 v[58:61], v[14:17], v[6:9], v[10:13]
	s_nop 4
	ds_read_b128 v[10:13], v113 offset:8704
	ds_read_b128 v[14:17], v113 offset:8768
	s_waitcnt lgkmcnt(1)
	v_mfma_f32_16x16x32_bf16 v[10:13], v[10:13], v[78:81], 0
	s_waitcnt lgkmcnt(0)
	v_mfma_f32_16x16x32_bf16 v[10:13], v[14:17], v[74:77], v[10:13]
	ds_read_b128 v[14:17], v113 offset:8832
	s_waitcnt lgkmcnt(0)
	v_mfma_f32_16x16x32_bf16 v[10:13], v[14:17], v[70:73], v[10:13]
	ds_read_b128 v[14:17], v113 offset:8896
	s_waitcnt lgkmcnt(0)
; #define LAS __attribute__((address_space(3)))
; __device__ __forceinline__ f32x4 mfma16(bf16x8 a, bf16x8 b, f32x4 c) { return __builtin_amdgcn_mfma_f32_16x16x32_bf16(a, b, c, 0, 0, 0); }
; __device__ __forceinline__ void attn_item(const P& p, const Ctx& c, int layer, int it, const bf16_t* Qp, int ldq, bf16_t* YM, int ldy, const bf16_t* Zp, int ldz) {
;     ...
; #pragma unroll
;         for (int mt = 0; mt < 16; ++mt) { acc[mt] = (f32x4){0.f, 0.f, 0.f, 0.f};
; #pragma unroll
;             for (int kk = 0; kk < 4; ++kk) { const bf16x8 a = *(const LAS bf16x8*)(Ks + (mt * 16 + l15) * 136 + kk * 32 + quad * 8); acc[mt] = mfma16(a, qf[kk], acc[mt]); }
;             if ((mt & 3) == 3) __builtin_amdgcn_sched_barrier(0); }
	v_mfma_f32_16x16x32_bf16 v[54:57], v[14:17], v[6:9], v[10:13]
	s_nop 4
	ds_read_b128 v[10:13], v113 offset:13056
	ds_read_b128 v[14:17], v113 offset:13120
	s_waitcnt lgkmcnt(1)
	v_mfma_f32_16x16x32_bf16 v[10:13], v[10:13], v[78:81], 0
	s_waitcnt lgkmcnt(0)
	v_mfma_f32_16x16x32_bf16 v[10:13], v[14:17], v[74:77], v[10:13]
	ds_read_b128 v[14:17], v113 offset:13184
	s_waitcnt lgkmcnt(0)
	v_mfma_f32_16x16x32_bf16 v[10:13], v[14:17], v[70:73], v[10:13]
	ds_read_b128 v[14:17], v113 offset:13248
	s_waitcnt lgkmcnt(0)
	v_mfma_f32_16x16x32_bf16 v[62:65], v[14:17], v[6:9], v[10:13]
	s_nop 4
	ds_read_b128 v[10:13], v113 offset:17408
	ds_read_b128 v[14:17], v113 offset:17472
	s_waitcnt lgkmcnt(1)
	v_mfma_f32_16x16x32_bf16 v[10:13], v[10:13], v[78:81], 0
	s_waitcnt lgkmcnt(0)
	v_mfma_f32_16x16x32_bf16 v[10:13], v[14:17], v[74:77], v[10:13]
	ds_read_b128 v[14:17], v113 offset:17536
	s_waitcnt lgkmcnt(0)
	v_mfma_f32_16x16x32_bf16 v[10:13], v[14:17], v[70:73], v[10:13]
	ds_read_b128 v[14:17], v113 offset:17600
	s_waitcnt lgkmcnt(0)
	v_mfma_f32_16x16x32_bf16 v[50:53], v[14:17], v[6:9], v[10:13]
	s_nop 4
	ds_read_b128 v[10:13], v113 offset:21760
	ds_read_b128 v[14:17], v113 offset:21824
	s_waitcnt lgkmcnt(1)
	v_mfma_f32_16x16x32_bf16 v[10:13], v[10:13], v[78:81], 0
	s_waitcnt lgkmcnt(0)
	v_mfma_f32_16x16x32_bf16 v[10:13], v[14:17], v[74:77], v[10:13]
	ds_read_b128 v[14:17], v113 offset:21888
	s_waitcnt lgkmcnt(0)
	v_mfma_f32_16x16x32_bf16 v[10:13], v[14:17], v[70:73], v[10:13]
	ds_read_b128 v[14:17], v113 offset:21952
	s_waitcnt lgkmcnt(0)
	v_mfma_f32_16x16x32_bf16 v[46:49], v[14:17], v[6:9], v[10:13]
	s_nop 4
	ds_read_b128 v[10:13], v113 offset:26112
	ds_read_b128 v[14:17], v113 offset:26176
	s_waitcnt lgkmcnt(1)
	v_mfma_f32_16x16x32_bf16 v[10:13], v[10:13], v[78:81], 0
	s_waitcnt lgkmcnt(0)
	v_mfma_f32_16x16x32_bf16 v[10:13], v[14:17], v[74:77], v[10:13]
	ds_read_b128 v[14:17], v113 offset:26240
	s_waitcnt lgkmcnt(0)
	v_mfma_f32_16x16x32_bf16 v[10:13], v[14:17], v[70:73], v[10:13]
	ds_read_b128 v[14:17], v113 offset:26304
	s_waitcnt lgkmcnt(0)
	v_mfma_f32_16x16x32_bf16 v[42:45], v[14:17], v[6:9], v[10:13]
	s_nop 4
	ds_read_b128 v[10:13], v113 offset:30464
	ds_read_b128 v[14:17], v113 offset:30528
	s_waitcnt lgkmcnt(1)
	v_mfma_f32_16x16x32_bf16 v[10:13], v[10:13], v[78:81], 0
	s_waitcnt lgkmcnt(0)
	v_mfma_f32_16x16x32_bf16 v[10:13], v[14:17], v[74:77], v[10:13]
	ds_read_b128 v[14:17], v113 offset:30592
	s_waitcnt lgkmcnt(0)
	v_mfma_f32_16x16x32_bf16 v[10:13], v[14:17], v[70:73], v[10:13]
	ds_read_b128 v[14:17], v113 offset:30656
	s_waitcnt lgkmcnt(0)
	v_mfma_f32_16x16x32_bf16 v[38:41], v[14:17], v[6:9], v[10:13]
	s_nop 4
	ds_read_b128 v[10:13], v113 offset:34816
	ds_read_b128 v[14:17], v113 offset:34880
	s_waitcnt lgkmcnt(1)
	v_mfma_f32_16x16x32_bf16 v[10:13], v[10:13], v[78:81], 0
	s_waitcnt lgkmcnt(0)
	v_mfma_f32_16x16x32_bf16 v[10:13], v[14:17], v[74:77], v[10:13]
	ds_read_b128 v[14:17], v113 offset:34944
	s_waitcnt lgkmcnt(0)
	v_mfma_f32_16x16x32_bf16 v[10:13], v[14:17], v[70:73], v[10:13]
	ds_read_b128 v[14:17], v113 offset:35008
	s_waitcnt lgkmcnt(0)
	v_mfma_f32_16x16x32_bf16 v[34:37], v[14:17], v[6:9], v[10:13]
	s_nop 4
	ds_read_b128 v[10:13], v113 offset:39168
	ds_read_b128 v[14:17], v113 offset:39232
	s_waitcnt lgkmcnt(1)
	v_mfma_f32_16x16x32_bf16 v[10:13], v[10:13], v[78:81], 0
	s_waitcnt lgkmcnt(0)
	v_mfma_f32_16x16x32_bf16 v[10:13], v[14:17], v[74:77], v[10:13]
	ds_read_b128 v[14:17], v113 offset:39296
	s_waitcnt lgkmcnt(0)
	v_mfma_f32_16x16x32_bf16 v[10:13], v[14:17], v[70:73], v[10:13]
	ds_read_b128 v[14:17], v113 offset:39360
	s_waitcnt lgkmcnt(0)
	v_mfma_f32_16x16x32_bf16 v[30:33], v[14:17], v[6:9], v[10:13]
	s_nop 4
	ds_read_b128 v[10:13], v113 offset:43520
	ds_read_b128 v[14:17], v113 offset:43584
	s_waitcnt lgkmcnt(1)
	v_mfma_f32_16x16x32_bf16 v[10:13], v[10:13], v[78:81], 0
	s_waitcnt lgkmcnt(0)
	v_mfma_f32_16x16x32_bf16 v[10:13], v[14:17], v[74:77], v[10:13]
	ds_read_b128 v[14:17], v113 offset:43648
	s_waitcnt lgkmcnt(0)
	v_mfma_f32_16x16x32_bf16 v[10:13], v[14:17], v[70:73], v[10:13]
	ds_read_b128 v[14:17], v113 offset:43712
	s_waitcnt lgkmcnt(0)
	v_mfma_f32_16x16x32_bf16 v[26:29], v[14:17], v[6:9], v[10:13]
	s_nop 4
	ds_read_b128 v[10:13], v113 offset:47872
	ds_read_b128 v[14:17], v113 offset:47936
	s_waitcnt lgkmcnt(1)
	v_mfma_f32_16x16x32_bf16 v[10:13], v[10:13], v[78:81], 0
	s_waitcnt lgkmcnt(0)
	v_mfma_f32_16x16x32_bf16 v[10:13], v[14:17], v[74:77], v[10:13]
	ds_read_b128 v[14:17], v113 offset:48000
	s_waitcnt lgkmcnt(0)
	v_mfma_f32_16x16x32_bf16 v[10:13], v[14:17], v[70:73], v[10:13]
	ds_read_b128 v[14:17], v113 offset:48064
	s_waitcnt lgkmcnt(0)
	v_mfma_f32_16x16x32_bf16 v[22:25], v[14:17], v[6:9], v[10:13]
	s_nop 4
	ds_read_b128 v[10:13], v113 offset:52224
	ds_read_b128 v[14:17], v113 offset:52288
	s_waitcnt lgkmcnt(1)
	v_mfma_f32_16x16x32_bf16 v[10:13], v[10:13], v[78:81], 0
	ds_read_b128 v[98:101], v113 offset:60992
	s_waitcnt lgkmcnt(1)
	v_mfma_f32_16x16x32_bf16 v[10:13], v[14:17], v[74:77], v[10:13]
	ds_read_b128 v[14:17], v113 offset:52352
	s_waitcnt lgkmcnt(0)
	v_mfma_f32_16x16x32_bf16 v[10:13], v[14:17], v[70:73], v[10:13]
	ds_read_b128 v[14:17], v113 offset:52416
	s_waitcnt lgkmcnt(0)
	v_mfma_f32_16x16x32_bf16 v[18:21], v[14:17], v[6:9], v[10:13]
	s_nop 4
	ds_read_b128 v[10:13], v113 offset:56576
	ds_read_b128 v[14:17], v113 offset:56640
	s_waitcnt lgkmcnt(1)
	v_mfma_f32_16x16x32_bf16 v[10:13], v[10:13], v[78:81], 0
	s_waitcnt lgkmcnt(0)
	v_mfma_f32_16x16x32_bf16 v[10:13], v[14:17], v[74:77], v[10:13]
	ds_read_b128 v[14:17], v113 offset:56704
	s_waitcnt lgkmcnt(0)
; __device__ __forceinline__ void attn_item(const P& p, const Ctx& c, int layer, int it, const bf16_t* Qp, int ldq, bf16_t* YM, int ldy, const bf16_t* Zp, int ldz) {
;     ...
;         float mx = -1e30f;
; #pragma unroll
;         for (int mt = 0; mt < 16; ++mt)
; #pragma unroll
;             for (int j = 0; j < 4; ++j) mx = fmaxf(mx, acc[mt][j]);
;         mx = fmaxf(mx, __shfl_xor(mx, 16)); mx = fmaxf(mx, __shfl_xor(mx, 32));
;         const float sc = 0.08838834764831845f * 1.4426950408889634f; float sm = 0.f;
; #pragma unroll
;         for (int mt = 0; mt < 16; ++mt)
; #pragma unroll
;             for (int j = 0; j < 4; ++j) { const float e = exp2f((acc[mt][j] - mx) * sc); acc[mt][j] = e; sm += e; }
	v_mfma_f32_16x16x32_bf16 v[10:13], v[14:17], v[70:73], v[10:13]
	ds_read_b128 v[14:17], v113 offset:56768
	s_waitcnt lgkmcnt(0)
	v_mfma_f32_16x16x32_bf16 v[14:17], v[14:17], v[6:9], v[10:13]
	s_nop 4
	ds_read_b128 v[10:13], v113 offset:60928
	s_waitcnt lgkmcnt(0)
	v_mfma_f32_16x16x32_bf16 v[10:13], v[10:13], v[78:81], 0
	v_mfma_f32_16x16x32_bf16 v[10:13], v[98:101], v[74:77], v[10:13]
	ds_read_b128 v[98:101], v113 offset:61056
	s_waitcnt lgkmcnt(0)
	v_mfma_f32_16x16x32_bf16 v[10:13], v[98:101], v[70:73], v[10:13]
	ds_read_b128 v[98:101], v113 offset:61120
	s_waitcnt lgkmcnt(0)
	v_mfma_f32_16x16x32_bf16 v[10:13], v[98:101], v[6:9], v[10:13]
	ds_read_b128 v[98:101], v113 offset:65280
	s_waitcnt lgkmcnt(0)
	v_mfma_f32_16x16x32_bf16 v[78:81], v[98:101], v[78:81], 0
	ds_read_b128 v[98:101], v113 offset:65344
	s_waitcnt lgkmcnt(0)
	v_mfma_f32_16x16x32_bf16 v[74:77], v[98:101], v[74:77], v[78:81]
	s_nop 4
	ds_read_b128 v[78:81], v113 offset:65408
	s_waitcnt lgkmcnt(0)
	v_mfma_f32_16x16x32_bf16 v[70:73], v[78:81], v[70:73], v[74:77]
	s_nop 2
	ds_read_b128 v[74:77], v113 offset:65472
	s_waitcnt lgkmcnt(0)
	v_mfma_f32_16x16x32_bf16 v[6:9], v[74:77], v[6:9], v[70:73]
	s_nop 2
	v_max3_f32 v70, v66, s14, v67
	v_max3_f32 v70, v70, v68, v69
	v_max3_f32 v70, v70, v58, v59
	v_max3_f32 v70, v70, v60, v61
	v_max3_f32 v70, v70, v54, v55
	v_max3_f32 v70, v70, v56, v57
	v_max3_f32 v70, v70, v62, v63
	v_max3_f32 v70, v70, v64, v65
	v_max3_f32 v70, v70, v50, v51
	v_max3_f32 v70, v70, v52, v53
	v_max3_f32 v70, v70, v46, v47
	v_max3_f32 v70, v70, v48, v49
	v_max3_f32 v70, v70, v42, v43
	v_max3_f32 v70, v70, v44, v45
	v_max3_f32 v70, v70, v38, v39
	v_max3_f32 v70, v70, v40, v41
	v_max3_f32 v70, v70, v34, v35
	v_max3_f32 v70, v70, v36, v37
	v_max3_f32 v70, v70, v30, v31
	v_max3_f32 v70, v70, v32, v33
	v_max3_f32 v70, v70, v26, v27
	v_max3_f32 v70, v70, v28, v29
	v_max3_f32 v70, v70, v22, v23
	v_max3_f32 v70, v70, v24, v25
	v_max3_f32 v70, v70, v18, v19
	v_max3_f32 v70, v70, v20, v21
	v_max3_f32 v70, v70, v14, v15
	v_max3_f32 v70, v70, v16, v17
	v_max3_f32 v70, v70, v10, v11
	v_max3_f32 v70, v70, v12, v13
	v_max3_f32 v70, v70, v6, v7
	v_max3_f32 v70, v70, v8, v9
	ds_bpermute_b32 v71, v108, v70
	s_waitcnt lgkmcnt(0)
	v_max_f32_e32 v71, v71, v71
	v_max_f32_e32 v70, v70, v71
	ds_bpermute_b32 v71, v109, v70
	s_waitcnt lgkmcnt(0)
	v_max_f32_e32 v71, v71, v71
	v_max_f32_e32 v87, v70, v71
	v_sub_f32_e32 v66, v66, v87
	v_mul_f32_e32 v70, 0x3e0293ee, v66
	v_cmp_gt_f32_e32 vcc, s59, v70
	v_sub_f32_e32 v67, v67, v87
	v_sub_f32_e32 v68, v68, v87
	v_cndmask_b32_e32 v70, 0, v215, vcc
	v_fmac_f32_e32 v70, 0x3e0293ee, v66
	v_exp_f32_e32 v66, v70
	v_cndmask_b32_e32 v70, 0, v216, vcc
	v_mul_f32_e32 v71, 0x3e0293ee, v68
	v_sub_f32_e32 v69, v69, v87
	v_ldexp_f32 v66, v66, v70
	v_mul_f32_e32 v70, 0x3e0293ee, v67
	v_cmp_gt_f32_e32 vcc, s59, v70
	v_sub_f32_e32 v58, v58, v87
	v_sub_f32_e32 v59, v59, v87
	v_cndmask_b32_e32 v70, 0, v215, vcc
	v_fmac_f32_e32 v70, 0x3e0293ee, v67
	v_exp_f32_e32 v67, v70
	v_cndmask_b32_e32 v70, 0, v216, vcc
	v_cmp_gt_f32_e32 vcc, s59, v71
	v_sub_f32_e32 v60, v60, v87
	v_sub_f32_e32 v61, v61, v87
	v_cndmask_b32_e32 v71, 0, v215, vcc
	v_fmac_f32_e32 v71, 0x3e0293ee, v68
	v_exp_f32_e32 v68, v71
	v_cndmask_b32_e32 v71, 0, v216, vcc
	v_sub_f32_e32 v54, v54, v87
	v_sub_f32_e32 v55, v55, v87
	v_ldexp_f32 v68, v68, v71
	v_mul_f32_e32 v71, 0x3e0293ee, v69
	v_cmp_gt_f32_e32 vcc, s59, v71
	v_sub_f32_e32 v56, v56, v87
	v_sub_f32_e32 v57, v57, v87
	v_cndmask_b32_e32 v71, 0, v215, vcc
	v_fmac_f32_e32 v71, 0x3e0293ee, v69
	v_exp_f32_e32 v69, v71
	v_cndmask_b32_e32 v71, 0, v216, vcc
	v_sub_f32_e32 v62, v62, v87
	v_sub_f32_e32 v63, v63, v87
	v_ldexp_f32 v69, v69, v71
	v_mul_f32_e32 v71, 0x3e0293ee, v58
	v_cmp_gt_f32_e32 vcc, s59, v71
	v_sub_f32_e32 v64, v64, v87
	v_sub_f32_e32 v65, v65, v87
	v_cndmask_b32_e32 v71, 0, v215, vcc
	v_fmac_f32_e32 v71, 0x3e0293ee, v58
	v_exp_f32_e32 v58, v71
	v_cndmask_b32_e32 v71, 0, v216, vcc
	v_sub_f32_e32 v50, v50, v87
	v_sub_f32_e32 v51, v51, v87
	v_ldexp_f32 v58, v58, v71
	v_mul_f32_e32 v71, 0x3e0293ee, v59
	v_cmp_gt_f32_e32 vcc, s59, v71
	v_sub_f32_e32 v52, v52, v87
	v_sub_f32_e32 v53, v53, v87
	v_cndmask_b32_e32 v71, 0, v215, vcc
	v_fmac_f32_e32 v71, 0x3e0293ee, v59
	v_exp_f32_e32 v59, v71
	v_cndmask_b32_e32 v71, 0, v216, vcc
	v_sub_f32_e32 v46, v46, v87
	v_sub_f32_e32 v47, v47, v87
	v_ldexp_f32 v59, v59, v71
	v_mul_f32_e32 v71, 0x3e0293ee, v60
	v_cmp_gt_f32_e32 vcc, s59, v71
	v_sub_f32_e32 v48, v48, v87
	v_sub_f32_e32 v49, v49, v87
	v_cndmask_b32_e32 v71, 0, v215, vcc
	v_fmac_f32_e32 v71, 0x3e0293ee, v60
	v_exp_f32_e32 v60, v71
	v_cndmask_b32_e32 v71, 0, v216, vcc
	v_sub_f32_e32 v42, v42, v87
	v_sub_f32_e32 v43, v43, v87
	v_ldexp_f32 v60, v60, v71
	v_mul_f32_e32 v71, 0x3e0293ee, v61
	v_cmp_gt_f32_e32 vcc, s59, v71
	v_sub_f32_e32 v44, v44, v87
	v_sub_f32_e32 v45, v45, v87
	v_cndmask_b32_e32 v71, 0, v215, vcc
	v_fmac_f32_e32 v71, 0x3e0293ee, v61
	v_exp_f32_e32 v61, v71
	v_cndmask_b32_e32 v71, 0, v216, vcc
	v_sub_f32_e32 v38, v38, v87
	v_sub_f32_e32 v39, v39, v87
	v_ldexp_f32 v61, v61, v71
	v_mul_f32_e32 v71, 0x3e0293ee, v54
	v_cmp_gt_f32_e32 vcc, s59, v71
	v_sub_f32_e32 v40, v40, v87
	v_sub_f32_e32 v41, v41, v87
	v_cndmask_b32_e32 v71, 0, v215, vcc
	v_fmac_f32_e32 v71, 0x3e0293ee, v54
	v_exp_f32_e32 v54, v71
	v_cndmask_b32_e32 v71, 0, v216, vcc
	v_ldexp_f32 v67, v67, v70
	v_add_f32_e32 v70, v66, v67
	v_ldexp_f32 v54, v54, v71
	v_mul_f32_e32 v71, 0x3e0293ee, v55
	v_cmp_gt_f32_e32 vcc, s59, v71
	v_sub_f32_e32 v34, v34, v87
	v_add_f32_e32 v70, v68, v70
	v_cndmask_b32_e32 v71, 0, v215, vcc
	v_fmac_f32_e32 v71, 0x3e0293ee, v55
	v_exp_f32_e32 v55, v71
; __device__ __forceinline__ void attn_item(const P& p, const Ctx& c, int layer, int it, const bf16_t* Qp, int ldq, bf16_t* YM, int ldy, const bf16_t* Zp, int ldz) {
;     ...
;         const float sc = 0.08838834764831845f * 1.4426950408889634f; float sm = 0.f;
; #pragma unroll
;         for (int mt = 0; mt < 16; ++mt)
; #pragma unroll
;             for (int j = 0; j < 4; ++j) { const float e = exp2f((acc[mt][j] - mx) * sc); acc[mt][j] = e; sm += e; }
	v_cndmask_b32_e32 v71, 0, v216, vcc
	v_add_f32_e32 v70, v69, v70
	v_add_f32_e32 v70, v58, v70
	v_ldexp_f32 v55, v55, v71
	v_mul_f32_e32 v71, 0x3e0293ee, v56
	v_cmp_gt_f32_e32 vcc, s59, v71
	v_add_f32_e32 v70, v59, v70
	v_add_f32_e32 v70, v60, v70
	v_cndmask_b32_e32 v71, 0, v215, vcc
	v_fmac_f32_e32 v71, 0x3e0293ee, v56
	v_exp_f32_e32 v56, v71
	v_cndmask_b32_e32 v71, 0, v216, vcc
	v_add_f32_e32 v70, v61, v70
	v_add_f32_e32 v70, v54, v70
	v_ldexp_f32 v56, v56, v71
	v_mul_f32_e32 v71, 0x3e0293ee, v57
	v_cmp_gt_f32_e32 vcc, s59, v71
	v_add_f32_e32 v70, v55, v70
	v_sub_f32_e32 v35, v35, v87
	v_cndmask_b32_e32 v71, 0, v215, vcc
	v_fmac_f32_e32 v71, 0x3e0293ee, v57
	v_exp_f32_e32 v57, v71
	v_cndmask_b32_e32 v71, 0, v216, vcc
	v_add_f32_e32 v70, v56, v70
	v_sub_f32_e32 v36, v36, v87
	v_ldexp_f32 v57, v57, v71
	v_mul_f32_e32 v71, 0x3e0293ee, v62
	v_cmp_gt_f32_e32 vcc, s59, v71
	v_add_f32_e32 v70, v57, v70
	v_sub_f32_e32 v37, v37, v87
	v_cndmask_b32_e32 v71, 0, v215, vcc
	v_fmac_f32_e32 v71, 0x3e0293ee, v62
	v_exp_f32_e32 v62, v71
	v_cndmask_b32_e32 v71, 0, v216, vcc
	v_sub_f32_e32 v30, v30, v87
	v_sub_f32_e32 v31, v31, v87
	v_ldexp_f32 v62, v62, v71
	v_mul_f32_e32 v71, 0x3e0293ee, v63
	v_cmp_gt_f32_e32 vcc, s59, v71
	v_add_f32_e32 v70, v62, v70
	v_sub_f32_e32 v26, v26, v87
	v_cndmask_b32_e32 v71, 0, v215, vcc
	v_fmac_f32_e32 v71, 0x3e0293ee, v63
	v_exp_f32_e32 v63, v71
	v_cndmask_b32_e32 v71, 0, v216, vcc
	v_sub_f32_e32 v27, v27, v87
	v_sub_f32_e32 v22, v22, v87
	v_ldexp_f32 v63, v63, v71
	v_mul_f32_e32 v71, 0x3e0293ee, v64
	v_cmp_gt_f32_e32 vcc, s59, v71
	v_add_f32_e32 v70, v63, v70
	v_sub_f32_e32 v23, v23, v87
	v_cndmask_b32_e32 v71, 0, v215, vcc
	v_fmac_f32_e32 v71, 0x3e0293ee, v64
	v_exp_f32_e32 v64, v71
	v_cndmask_b32_e32 v71, 0, v216, vcc
	v_sub_f32_e32 v18, v18, v87
	v_sub_f32_e32 v19, v19, v87
	v_ldexp_f32 v64, v64, v71
	v_mul_f32_e32 v71, 0x3e0293ee, v65
	v_cmp_gt_f32_e32 vcc, s59, v71
	v_add_f32_e32 v70, v64, v70
	v_sub_f32_e32 v14, v14, v87
	v_cndmask_b32_e32 v71, 0, v215, vcc
	v_fmac_f32_e32 v71, 0x3e0293ee, v65
	v_exp_f32_e32 v65, v71
	v_cndmask_b32_e32 v71, 0, v216, vcc
	v_sub_f32_e32 v15, v15, v87
	v_sub_f32_e32 v10, v10, v87
	v_ldexp_f32 v65, v65, v71
	v_mul_f32_e32 v71, 0x3e0293ee, v50
	v_cmp_gt_f32_e32 vcc, s59, v71
	v_add_f32_e32 v70, v65, v70
	v_sub_f32_e32 v11, v11, v87
	v_cndmask_b32_e32 v71, 0, v215, vcc
	v_fmac_f32_e32 v71, 0x3e0293ee, v50
	v_exp_f32_e32 v50, v71
	v_cndmask_b32_e32 v71, 0, v216, vcc
	v_sub_f32_e32 v6, v6, v87
	v_sub_f32_e32 v7, v7, v87
	v_ldexp_f32 v50, v50, v71
	v_mul_f32_e32 v71, 0x3e0293ee, v51
	v_cmp_gt_f32_e32 vcc, s59, v71
	v_add_f32_e32 v70, v50, v70
	s_nop 0
	v_cndmask_b32_e32 v71, 0, v215, vcc
	v_fmac_f32_e32 v71, 0x3e0293ee, v51
	v_exp_f32_e32 v51, v71
	v_cndmask_b32_e32 v71, 0, v216, vcc
	v_ldexp_f32 v51, v51, v71
	v_mul_f32_e32 v71, 0x3e0293ee, v52
	v_cmp_gt_f32_e32 vcc, s59, v71
	v_add_f32_e32 v70, v51, v70
	s_nop 0
	v_cndmask_b32_e32 v71, 0, v215, vcc
	v_fmac_f32_e32 v71, 0x3e0293ee, v52
	v_exp_f32_e32 v52, v71
	v_cndmask_b32_e32 v71, 0, v216, vcc
	v_ldexp_f32 v52, v52, v71
	v_mul_f32_e32 v71, 0x3e0293ee, v53
	v_cmp_gt_f32_e32 vcc, s59, v71
	v_add_f32_e32 v70, v52, v70
	s_nop 0
	v_cndmask_b32_e32 v71, 0, v215, vcc
	v_fmac_f32_e32 v71, 0x3e0293ee, v53
	v_exp_f32_e32 v53, v71
	v_cndmask_b32_e32 v71, 0, v216, vcc
	v_ldexp_f32 v53, v53, v71
	v_mul_f32_e32 v71, 0x3e0293ee, v46
	v_cmp_gt_f32_e32 vcc, s59, v71
	v_add_f32_e32 v70, v53, v70
	s_nop 0
	v_cndmask_b32_e32 v71, 0, v215, vcc
	v_fmac_f32_e32 v71, 0x3e0293ee, v46
	v_exp_f32_e32 v46, v71
	v_cndmask_b32_e32 v71, 0, v216, vcc
	v_ldexp_f32 v46, v46, v71
	v_mul_f32_e32 v71, 0x3e0293ee, v47
	v_cmp_gt_f32_e32 vcc, s59, v71
	v_add_f32_e32 v70, v46, v70
	s_nop 0
	v_cndmask_b32_e32 v71, 0, v215, vcc
	v_fmac_f32_e32 v71, 0x3e0293ee, v47
	v_exp_f32_e32 v47, v71
	v_cndmask_b32_e32 v71, 0, v216, vcc
	v_ldexp_f32 v47, v47, v71
	v_mul_f32_e32 v71, 0x3e0293ee, v48
	v_cmp_gt_f32_e32 vcc, s59, v71
	v_add_f32_e32 v70, v47, v70
	s_nop 0
	v_cndmask_b32_e32 v71, 0, v215, vcc
	v_fmac_f32_e32 v71, 0x3e0293ee, v48
	v_exp_f32_e32 v48, v71
	v_cndmask_b32_e32 v71, 0, v216, vcc
	v_ldexp_f32 v48, v48, v71
	v_mul_f32_e32 v71, 0x3e0293ee, v49
	v_cmp_gt_f32_e32 vcc, s59, v71
	v_add_f32_e32 v70, v48, v70
	s_nop 0
	v_cndmask_b32_e32 v71, 0, v215, vcc
	v_fmac_f32_e32 v71, 0x3e0293ee, v49
	v_exp_f32_e32 v49, v71
	v_cndmask_b32_e32 v71, 0, v216, vcc
	v_ldexp_f32 v49, v49, v71
	v_mul_f32_e32 v71, 0x3e0293ee, v42
	v_cmp_gt_f32_e32 vcc, s59, v71
	v_add_f32_e32 v70, v49, v70
	s_nop 0
	v_cndmask_b32_e32 v71, 0, v215, vcc
	v_fmac_f32_e32 v71, 0x3e0293ee, v42
	v_exp_f32_e32 v42, v71
	v_cndmask_b32_e32 v71, 0, v216, vcc
	v_ldexp_f32 v42, v42, v71
	v_mul_f32_e32 v71, 0x3e0293ee, v43
	v_cmp_gt_f32_e32 vcc, s59, v71
	v_add_f32_e32 v70, v42, v70
	s_nop 0
	v_cndmask_b32_e32 v71, 0, v215, vcc
	v_fmac_f32_e32 v71, 0x3e0293ee, v43
	v_exp_f32_e32 v43, v71
	v_cndmask_b32_e32 v71, 0, v216, vcc
	v_ldexp_f32 v43, v43, v71
	v_mul_f32_e32 v71, 0x3e0293ee, v44
	v_cmp_gt_f32_e32 vcc, s59, v71
	v_add_f32_e32 v70, v43, v70
	s_nop 0
	v_cndmask_b32_e32 v71, 0, v215, vcc
	v_fmac_f32_e32 v71, 0x3e0293ee, v44
	v_exp_f32_e32 v44, v71
	v_cndmask_b32_e32 v71, 0, v216, vcc
	v_ldexp_f32 v44, v44, v71
	v_mul_f32_e32 v71, 0x3e0293ee, v45
	v_cmp_gt_f32_e32 vcc, s59, v71
	v_add_f32_e32 v70, v44, v70
	s_nop 0
	v_cndmask_b32_e32 v71, 0, v215, vcc
	v_fmac_f32_e32 v71, 0x3e0293ee, v45
	v_exp_f32_e32 v45, v71
	v_cndmask_b32_e32 v71, 0, v216, vcc
	v_ldexp_f32 v45, v45, v71
	v_mul_f32_e32 v71, 0x3e0293ee, v38
	v_cmp_gt_f32_e32 vcc, s59, v71
	v_add_f32_e32 v70, v45, v70
	s_nop 0
	v_cndmask_b32_e32 v71, 0, v215, vcc
; __device__ __forceinline__ void attn_item(const P& p, const Ctx& c, int layer, int it, const bf16_t* Qp, int ldq, bf16_t* YM, int ldy, const bf16_t* Zp, int ldz) {
;     ...
;         const float sc = 0.08838834764831845f * 1.4426950408889634f; float sm = 0.f;
; #pragma unroll
;         for (int mt = 0; mt < 16; ++mt)
; #pragma unroll
;             for (int j = 0; j < 4; ++j) { const float e = exp2f((acc[mt][j] - mx) * sc); acc[mt][j] = e; sm += e; }
	v_fmac_f32_e32 v71, 0x3e0293ee, v38
	v_exp_f32_e32 v38, v71
	v_cndmask_b32_e32 v71, 0, v216, vcc
	v_ldexp_f32 v38, v38, v71
	v_mul_f32_e32 v71, 0x3e0293ee, v39
	v_cmp_gt_f32_e32 vcc, s59, v71
	v_add_f32_e32 v70, v38, v70
	s_nop 0
	v_cndmask_b32_e32 v71, 0, v215, vcc
	v_fmac_f32_e32 v71, 0x3e0293ee, v39
	v_exp_f32_e32 v39, v71
	v_cndmask_b32_e32 v71, 0, v216, vcc
	v_ldexp_f32 v39, v39, v71
	v_mul_f32_e32 v71, 0x3e0293ee, v40
	v_cmp_gt_f32_e32 vcc, s59, v71
	v_add_f32_e32 v70, v39, v70
	s_nop 0
	v_cndmask_b32_e32 v71, 0, v215, vcc
	v_fmac_f32_e32 v71, 0x3e0293ee, v40
	v_exp_f32_e32 v40, v71
	v_cndmask_b32_e32 v71, 0, v216, vcc
	v_ldexp_f32 v40, v40, v71
	v_mul_f32_e32 v71, 0x3e0293ee, v41
	v_cmp_gt_f32_e32 vcc, s59, v71
	v_add_f32_e32 v70, v40, v70
	s_nop 0
	v_cndmask_b32_e32 v71, 0, v215, vcc
	v_fmac_f32_e32 v71, 0x3e0293ee, v41
	v_exp_f32_e32 v41, v71
	v_cndmask_b32_e32 v71, 0, v216, vcc
	v_ldexp_f32 v41, v41, v71
	v_mul_f32_e32 v71, 0x3e0293ee, v34
	v_cmp_gt_f32_e32 vcc, s59, v71
	v_add_f32_e32 v70, v41, v70
	s_nop 0
	v_cndmask_b32_e32 v71, 0, v215, vcc
	v_fmac_f32_e32 v71, 0x3e0293ee, v34
	v_exp_f32_e32 v34, v71
	v_cndmask_b32_e32 v71, 0, v216, vcc
	v_ldexp_f32 v34, v34, v71
	v_mul_f32_e32 v71, 0x3e0293ee, v35
	v_cmp_gt_f32_e32 vcc, s59, v71
	v_add_f32_e32 v70, v34, v70
	s_nop 0
	v_cndmask_b32_e32 v71, 0, v215, vcc
	v_fmac_f32_e32 v71, 0x3e0293ee, v35
	v_exp_f32_e32 v35, v71
	v_cndmask_b32_e32 v71, 0, v216, vcc
	v_ldexp_f32 v35, v35, v71
	v_mul_f32_e32 v71, 0x3e0293ee, v36
	v_cmp_gt_f32_e32 vcc, s59, v71
	v_add_f32_e32 v70, v35, v70
	s_nop 0
	v_cndmask_b32_e32 v71, 0, v215, vcc
	v_fmac_f32_e32 v71, 0x3e0293ee, v36
	v_exp_f32_e32 v36, v71
	v_cndmask_b32_e32 v71, 0, v216, vcc
	v_ldexp_f32 v36, v36, v71
	v_mul_f32_e32 v71, 0x3e0293ee, v37
	v_cmp_gt_f32_e32 vcc, s59, v71
	v_add_f32_e32 v70, v36, v70
	s_nop 0
	v_cndmask_b32_e32 v71, 0, v215, vcc
	v_fmac_f32_e32 v71, 0x3e0293ee, v37
	v_exp_f32_e32 v37, v71
	v_cndmask_b32_e32 v71, 0, v216, vcc
	v_ldexp_f32 v37, v37, v71
	v_add_f32_e32 v71, v37, v70
	v_mul_f32_e32 v70, 0x3e0293ee, v30
	v_cmp_gt_f32_e32 vcc, s59, v70
	s_nop 1
	v_cndmask_b32_e32 v70, 0, v215, vcc
	v_fmac_f32_e32 v70, 0x3e0293ee, v30
	v_exp_f32_e32 v30, v70
	v_cndmask_b32_e32 v70, 0, v216, vcc
	v_ldexp_f32 v70, v30, v70
	v_add_f32_e32 v30, v70, v71
	v_mul_f32_e32 v71, 0x3e0293ee, v31
	v_cmp_gt_f32_e32 vcc, s59, v71
	s_nop 1
	v_cndmask_b32_e32 v71, 0, v215, vcc
	v_fmac_f32_e32 v71, 0x3e0293ee, v31
	v_exp_f32_e32 v31, v71
	v_cndmask_b32_e32 v71, 0, v216, vcc
	v_ldexp_f32 v71, v31, v71
	v_sub_f32_e32 v31, v32, v87
	v_mul_f32_e32 v32, 0x3e0293ee, v31
	v_cmp_gt_f32_e32 vcc, s59, v32
	v_add_f32_e32 v30, v71, v30
	s_nop 0
	v_cndmask_b32_e32 v32, 0, v215, vcc
	v_fmac_f32_e32 v32, 0x3e0293ee, v31
	v_exp_f32_e32 v31, v32
	v_cndmask_b32_e32 v32, 0, v216, vcc
	v_ldexp_f32 v72, v31, v32
	v_sub_f32_e32 v31, v33, v87
	v_mul_f32_e32 v32, 0x3e0293ee, v31
	v_cmp_gt_f32_e32 vcc, s59, v32
	v_add_f32_e32 v30, v72, v30
	s_nop 0
	v_cndmask_b32_e32 v32, 0, v215, vcc
	v_fmac_f32_e32 v32, 0x3e0293ee, v31
	v_exp_f32_e32 v31, v32
	v_cndmask_b32_e32 v32, 0, v216, vcc
	v_ldexp_f32 v73, v31, v32
	v_mul_f32_e32 v31, 0x3e0293ee, v26
	v_cmp_gt_f32_e32 vcc, s59, v31
	v_add_f32_e32 v30, v73, v30
	s_nop 0
	v_cndmask_b32_e32 v31, 0, v215, vcc
	v_fmac_f32_e32 v31, 0x3e0293ee, v26
	v_exp_f32_e32 v26, v31
	v_cndmask_b32_e32 v31, 0, v216, vcc
	v_ldexp_f32 v74, v26, v31
	v_add_f32_e32 v26, v74, v30
	v_mul_f32_e32 v30, 0x3e0293ee, v27
	v_cmp_gt_f32_e32 vcc, s59, v30
	s_nop 1
	v_cndmask_b32_e32 v30, 0, v215, vcc
	v_fmac_f32_e32 v30, 0x3e0293ee, v27
	v_exp_f32_e32 v27, v30
	v_cndmask_b32_e32 v30, 0, v216, vcc
	v_ldexp_f32 v75, v27, v30
	v_sub_f32_e32 v27, v28, v87
	v_mul_f32_e32 v28, 0x3e0293ee, v27
	v_cmp_gt_f32_e32 vcc, s59, v28
	v_add_f32_e32 v26, v75, v26
	s_nop 0
	v_cndmask_b32_e32 v28, 0, v215, vcc
	v_fmac_f32_e32 v28, 0x3e0293ee, v27
	v_exp_f32_e32 v27, v28
	v_cndmask_b32_e32 v28, 0, v216, vcc
	v_ldexp_f32 v76, v27, v28
	v_sub_f32_e32 v27, v29, v87
	v_mul_f32_e32 v28, 0x3e0293ee, v27
	v_cmp_gt_f32_e32 vcc, s59, v28
	v_add_f32_e32 v26, v76, v26
	s_nop 0
	v_cndmask_b32_e32 v28, 0, v215, vcc
	v_fmac_f32_e32 v28, 0x3e0293ee, v27
	v_exp_f32_e32 v27, v28
	v_cndmask_b32_e32 v28, 0, v216, vcc
	v_ldexp_f32 v77, v27, v28
	v_mul_f32_e32 v27, 0x3e0293ee, v22
	v_cmp_gt_f32_e32 vcc, s59, v27
	v_add_f32_e32 v26, v77, v26
	s_nop 0
	v_cndmask_b32_e32 v27, 0, v215, vcc
	v_fmac_f32_e32 v27, 0x3e0293ee, v22
	v_exp_f32_e32 v22, v27
	v_cndmask_b32_e32 v27, 0, v216, vcc
	v_ldexp_f32 v78, v22, v27
	v_add_f32_e32 v22, v78, v26
	v_mul_f32_e32 v26, 0x3e0293ee, v23
	v_cmp_gt_f32_e32 vcc, s59, v26
	s_nop 1
	v_cndmask_b32_e32 v26, 0, v215, vcc
	v_fmac_f32_e32 v26, 0x3e0293ee, v23
	v_exp_f32_e32 v23, v26
	v_cndmask_b32_e32 v26, 0, v216, vcc
	v_ldexp_f32 v79, v23, v26
	v_sub_f32_e32 v23, v24, v87
	v_mul_f32_e32 v24, 0x3e0293ee, v23
	v_cmp_gt_f32_e32 vcc, s59, v24
	v_add_f32_e32 v22, v79, v22
	s_nop 0
	v_cndmask_b32_e32 v24, 0, v215, vcc
	v_fmac_f32_e32 v24, 0x3e0293ee, v23
	v_exp_f32_e32 v23, v24
	v_cndmask_b32_e32 v24, 0, v216, vcc
	v_ldexp_f32 v80, v23, v24
	v_sub_f32_e32 v23, v25, v87
	v_mul_f32_e32 v24, 0x3e0293ee, v23
	v_cmp_gt_f32_e32 vcc, s59, v24
	v_add_f32_e32 v22, v80, v22
	s_nop 0
	v_cndmask_b32_e32 v24, 0, v215, vcc
	v_fmac_f32_e32 v24, 0x3e0293ee, v23
	v_exp_f32_e32 v23, v24
	v_cndmask_b32_e32 v24, 0, v216, vcc
	v_ldexp_f32 v81, v23, v24
	v_mul_f32_e32 v23, 0x3e0293ee, v18
	v_cmp_gt_f32_e32 vcc, s59, v23
	v_add_f32_e32 v22, v81, v22
	s_nop 0
	v_cndmask_b32_e32 v23, 0, v215, vcc
	v_fmac_f32_e32 v23, 0x3e0293ee, v18
	v_exp_f32_e32 v18, v23
	v_cndmask_b32_e32 v23, 0, v216, vcc
; __device__ __forceinline__ void attn_item(const P& p, const Ctx& c, int layer, int it, const bf16_t* Qp, int ldq, bf16_t* YM, int ldy, const bf16_t* Zp, int ldz) {
;     ...
;         const float sc = 0.08838834764831845f * 1.4426950408889634f; float sm = 0.f;
; #pragma unroll
;         for (int mt = 0; mt < 16; ++mt)
; #pragma unroll
;             for (int j = 0; j < 4; ++j) { const float e = exp2f((acc[mt][j] - mx) * sc); acc[mt][j] = e; sm += e; }
;         sm += __shfl_xor(sm, 16); sm += __shfl_xor(sm, 32);
	v_ldexp_f32 v98, v18, v23
	v_add_f32_e32 v18, v98, v22
	v_mul_f32_e32 v22, 0x3e0293ee, v19
	v_cmp_gt_f32_e32 vcc, s59, v22
	s_nop 1
	v_cndmask_b32_e32 v22, 0, v215, vcc
	v_fmac_f32_e32 v22, 0x3e0293ee, v19
	v_exp_f32_e32 v19, v22
	v_cndmask_b32_e32 v22, 0, v216, vcc
	v_ldexp_f32 v99, v19, v22
	v_sub_f32_e32 v19, v20, v87
	v_mul_f32_e32 v20, 0x3e0293ee, v19
	v_cmp_gt_f32_e32 vcc, s59, v20
	v_add_f32_e32 v18, v99, v18
	s_nop 0
	v_cndmask_b32_e32 v20, 0, v215, vcc
	v_fmac_f32_e32 v20, 0x3e0293ee, v19
	v_exp_f32_e32 v19, v20
	v_cndmask_b32_e32 v20, 0, v216, vcc
	v_ldexp_f32 v100, v19, v20
	v_sub_f32_e32 v19, v21, v87
	v_mul_f32_e32 v20, 0x3e0293ee, v19
	v_cmp_gt_f32_e32 vcc, s59, v20
	v_add_f32_e32 v18, v100, v18
	s_nop 0
	v_cndmask_b32_e32 v20, 0, v215, vcc
	v_fmac_f32_e32 v20, 0x3e0293ee, v19
	v_exp_f32_e32 v19, v20
	v_cndmask_b32_e32 v20, 0, v216, vcc
	v_ldexp_f32 v101, v19, v20
	v_mul_f32_e32 v19, 0x3e0293ee, v14
	v_cmp_gt_f32_e32 vcc, s59, v19
	v_add_f32_e32 v18, v101, v18
	s_nop 0
	v_cndmask_b32_e32 v19, 0, v215, vcc
	v_fmac_f32_e32 v19, 0x3e0293ee, v14
	v_exp_f32_e32 v14, v19
	v_cndmask_b32_e32 v19, 0, v216, vcc
	v_ldexp_f32 v102, v14, v19
	v_add_f32_e32 v14, v102, v18
	v_mul_f32_e32 v18, 0x3e0293ee, v15
	v_cmp_gt_f32_e32 vcc, s59, v18
	s_nop 1
	v_cndmask_b32_e32 v18, 0, v215, vcc
	v_fmac_f32_e32 v18, 0x3e0293ee, v15
	v_exp_f32_e32 v15, v18
	v_cndmask_b32_e32 v18, 0, v216, vcc
	v_ldexp_f32 v103, v15, v18
	v_sub_f32_e32 v15, v16, v87
	v_mul_f32_e32 v16, 0x3e0293ee, v15
	v_cmp_gt_f32_e32 vcc, s59, v16
	v_add_f32_e32 v14, v103, v14
	s_nop 0
	v_cndmask_b32_e32 v16, 0, v215, vcc
	v_fmac_f32_e32 v16, 0x3e0293ee, v15
	v_exp_f32_e32 v15, v16
	v_cndmask_b32_e32 v16, 0, v216, vcc
	v_ldexp_f32 v104, v15, v16
	v_sub_f32_e32 v15, v17, v87
	v_mul_f32_e32 v16, 0x3e0293ee, v15
	v_cmp_gt_f32_e32 vcc, s59, v16
	v_add_f32_e32 v14, v104, v14
	s_nop 0
	v_cndmask_b32_e32 v16, 0, v215, vcc
	v_fmac_f32_e32 v16, 0x3e0293ee, v15
	v_exp_f32_e32 v15, v16
	v_cndmask_b32_e32 v16, 0, v216, vcc
	v_ldexp_f32 v105, v15, v16
	v_mul_f32_e32 v15, 0x3e0293ee, v10
	v_cmp_gt_f32_e32 vcc, s59, v15
	v_add_f32_e32 v14, v105, v14
	s_nop 0
	v_cndmask_b32_e32 v15, 0, v215, vcc
	v_fmac_f32_e32 v15, 0x3e0293ee, v10
	v_exp_f32_e32 v10, v15
	v_cndmask_b32_e32 v15, 0, v216, vcc
	v_ldexp_f32 v106, v10, v15
	v_add_f32_e32 v10, v106, v14
	v_mul_f32_e32 v14, 0x3e0293ee, v11
	v_cmp_gt_f32_e32 vcc, s59, v14
	s_nop 1
	v_cndmask_b32_e32 v14, 0, v215, vcc
	v_fmac_f32_e32 v14, 0x3e0293ee, v11
	v_exp_f32_e32 v11, v14
	v_cndmask_b32_e32 v14, 0, v216, vcc
	v_ldexp_f32 v107, v11, v14
	v_sub_f32_e32 v11, v12, v87
	v_mul_f32_e32 v12, 0x3e0293ee, v11
	v_cmp_gt_f32_e32 vcc, s59, v12
	v_add_f32_e32 v10, v107, v10
	s_nop 0
	v_cndmask_b32_e32 v12, 0, v215, vcc
	v_fmac_f32_e32 v12, 0x3e0293ee, v11
	v_exp_f32_e32 v11, v12
	v_cndmask_b32_e32 v12, 0, v216, vcc
	v_ldexp_f32 v116, v11, v12
	v_sub_f32_e32 v11, v13, v87
	v_mul_f32_e32 v12, 0x3e0293ee, v11
	v_cmp_gt_f32_e32 vcc, s59, v12
	v_add_f32_e32 v10, v116, v10
	s_nop 0
	v_cndmask_b32_e32 v12, 0, v215, vcc
	v_fmac_f32_e32 v12, 0x3e0293ee, v11
	v_exp_f32_e32 v11, v12
	v_cndmask_b32_e32 v12, 0, v216, vcc
	v_ldexp_f32 v117, v11, v12
	v_mul_f32_e32 v11, 0x3e0293ee, v6
	v_cmp_gt_f32_e32 vcc, s59, v11
	v_add_f32_e32 v10, v117, v10
	s_nop 0
	v_cndmask_b32_e32 v11, 0, v215, vcc
	v_fmac_f32_e32 v11, 0x3e0293ee, v6
	v_exp_f32_e32 v6, v11
	v_cndmask_b32_e32 v11, 0, v216, vcc
	v_ldexp_f32 v118, v6, v11
	v_add_f32_e32 v6, v118, v10
	v_mul_f32_e32 v10, 0x3e0293ee, v7
	v_cmp_gt_f32_e32 vcc, s59, v10
	s_nop 1
	v_cndmask_b32_e32 v10, 0, v215, vcc
	v_fmac_f32_e32 v10, 0x3e0293ee, v7
	v_exp_f32_e32 v7, v10
	v_cndmask_b32_e32 v10, 0, v216, vcc
	v_ldexp_f32 v119, v7, v10
	v_sub_f32_e32 v7, v8, v87
	v_mul_f32_e32 v8, 0x3e0293ee, v7
	v_cmp_gt_f32_e32 vcc, s59, v8
	v_add_f32_e32 v6, v119, v6
	s_nop 0
	v_cndmask_b32_e32 v8, 0, v215, vcc
	v_fmac_f32_e32 v8, 0x3e0293ee, v7
	v_exp_f32_e32 v7, v8
	v_cndmask_b32_e32 v8, 0, v216, vcc
	v_ldexp_f32 v120, v7, v8
	v_sub_f32_e32 v7, v9, v87
	v_mul_f32_e32 v8, 0x3e0293ee, v7
	v_cmp_gt_f32_e32 vcc, s59, v8
	v_add_f32_e32 v6, v120, v6
	s_nop 0
	v_cndmask_b32_e32 v8, 0, v215, vcc
	v_fmac_f32_e32 v8, 0x3e0293ee, v7
	v_exp_f32_e32 v7, v8
	v_cndmask_b32_e32 v8, 0, v216, vcc
	v_ldexp_f32 v121, v7, v8
	v_add_f32_e32 v6, v121, v6
	ds_bpermute_b32 v7, v108, v6
	s_waitcnt lgkmcnt(0)
	v_add_f32_e32 v6, v6, v7
	ds_bpermute_b32 v7, v109, v6
	s_waitcnt lgkmcnt(0)
; #define LAS __attribute__((address_space(3)))
; __device__ __forceinline__ unsigned pk2(float lo, float hi) { const bf2_t r = __builtin_convertvector((f32x2){lo, hi}, bf2_t); unsigned u; __builtin_memcpy(&u, &r, 4); return u; }
; __device__ __forceinline__ float frcp(float x) { return __builtin_amdgcn_rcpf(x); }
; __device__ __forceinline__ f32x4 mfma16(bf16x8 a, bf16x8 b, f32x4 c) { return __builtin_amdgcn_mfma_f32_16x16x32_bf16(a, b, c, 0, 0, 0); }
; __device__ __forceinline__ void attn_item(const P& p, const Ctx& c, int layer, int it, const bf16_t* Qp, int ldq, bf16_t* YM, int ldy, const bf16_t* Zp, int ldz) {
;     ...
;         const float inv = frcp(sm);
;         bf16x8 pa[8];
; #pragma unroll
;         for (int kp = 0; kp < 8; ++kp) {
;             u32x4 aw; aw.x = pk2(acc[2 * kp][0] * inv, acc[2 * kp][1] * inv); aw.y = pk2(acc[2 * kp][2] * inv, acc[2 * kp][3] * inv);
;             aw.z = pk2(acc[2 * kp + 1][0] * inv, acc[2 * kp + 1][1] * inv); aw.w = pk2(acc[2 * kp + 1][2] * inv, acc[2 * kp + 1][3] * inv);
;             __builtin_memcpy(&pa[kp], &aw, 16); }
;         __builtin_amdgcn_sched_barrier(0);
;         f32x4 o[8];
; #pragma unroll
;         for (int nt = 0; nt < 8; ++nt) o[nt] = (f32x4){0.f, 0.f, 0.f, 0.f};
; #pragma unroll
;         for (int kp = 0; kp < 8; ++kp) {
;             const bf16x8 a = pa[kp];
; #pragma unroll
;             for (int nt = 0; nt < 8; ++nt) { const LAS bf16_t* vp = Vs + (nt * 16 + l15) * 264 + 2 * kp * 16 + quad * 4;
;                 const u32x2 lo = *(const LAS u32x2*)vp, hi = *(const LAS u32x2*)(vp + 16); u32x4 bw = (u32x4){lo.x, lo.y, hi.x, hi.y}; bf16x8 bfr; __builtin_memcpy(&bfr, &bw, 16);
;                 o[nt] = mfma16(a, bfr, o[nt]); }
;             __builtin_amdgcn_sched_barrier(0);
;         }
	v_add_f32_e32 v6, v6, v7
	v_rcp_f32_e32 v122, v6
	s_nop 0
	v_pk_mul_f32 v[6:7], v[66:67], v[122:123] op_sel_hi:[1,0]
	s_nop 0
	v_cvt_pk_bf16_f32 v66, v6, v7
	v_pk_mul_f32 v[6:7], v[68:69], v[122:123] op_sel_hi:[1,0]
	v_pk_mul_f32 v[8:9], v[116:117], v[122:123] op_sel_hi:[1,0]
	v_cvt_pk_bf16_f32 v67, v6, v7
	v_pk_mul_f32 v[6:7], v[58:59], v[122:123] op_sel_hi:[1,0]
	s_nop 0
	v_cvt_pk_bf16_f32 v68, v6, v7
	v_pk_mul_f32 v[6:7], v[60:61], v[122:123] op_sel_hi:[1,0]
	s_nop 0
	v_cvt_pk_bf16_f32 v69, v6, v7
	v_pk_mul_f32 v[6:7], v[54:55], v[122:123] op_sel_hi:[1,0]
	s_nop 0
	v_cvt_pk_bf16_f32 v30, v6, v7
	v_pk_mul_f32 v[6:7], v[56:57], v[122:123] op_sel_hi:[1,0]
	s_nop 0
	v_cvt_pk_bf16_f32 v31, v6, v7
	v_pk_mul_f32 v[6:7], v[62:63], v[122:123] op_sel_hi:[1,0]
	s_nop 0
	v_cvt_pk_bf16_f32 v32, v6, v7
	v_pk_mul_f32 v[6:7], v[64:65], v[122:123] op_sel_hi:[1,0]
	s_nop 0
	v_cvt_pk_bf16_f32 v33, v6, v7
	v_pk_mul_f32 v[6:7], v[50:51], v[122:123] op_sel_hi:[1,0]
	s_nop 0
	v_cvt_pk_bf16_f32 v26, v6, v7
	v_pk_mul_f32 v[6:7], v[52:53], v[122:123] op_sel_hi:[1,0]
	s_nop 0
	v_cvt_pk_bf16_f32 v27, v6, v7
	v_pk_mul_f32 v[6:7], v[46:47], v[122:123] op_sel_hi:[1,0]
	s_nop 0
	v_cvt_pk_bf16_f32 v28, v6, v7
	v_pk_mul_f32 v[6:7], v[48:49], v[122:123] op_sel_hi:[1,0]
	s_nop 0
	v_cvt_pk_bf16_f32 v29, v6, v7
	v_pk_mul_f32 v[6:7], v[42:43], v[122:123] op_sel_hi:[1,0]
	s_nop 0
	v_cvt_pk_bf16_f32 v22, v6, v7
	v_pk_mul_f32 v[6:7], v[44:45], v[122:123] op_sel_hi:[1,0]
	s_nop 0
	v_cvt_pk_bf16_f32 v23, v6, v7
	v_pk_mul_f32 v[6:7], v[38:39], v[122:123] op_sel_hi:[1,0]
	s_nop 0
	v_cvt_pk_bf16_f32 v24, v6, v7
	v_pk_mul_f32 v[6:7], v[40:41], v[122:123] op_sel_hi:[1,0]
	s_nop 0
	v_cvt_pk_bf16_f32 v25, v6, v7
	v_pk_mul_f32 v[6:7], v[34:35], v[122:123] op_sel_hi:[1,0]
	v_pk_mul_f32 v[34:35], v[120:121], v[122:123] op_sel_hi:[1,0]
	v_cvt_pk_bf16_f32 v18, v6, v7
	v_pk_mul_f32 v[6:7], v[36:37], v[122:123] op_sel_hi:[1,0]
	s_nop 0
	v_cvt_pk_bf16_f32 v19, v6, v7
	v_pk_mul_f32 v[6:7], v[70:71], v[122:123] op_sel_hi:[1,0]
	s_nop 0
	v_cvt_pk_bf16_f32 v20, v6, v7
	v_pk_mul_f32 v[6:7], v[72:73], v[122:123] op_sel_hi:[1,0]
	s_nop 0
	v_cvt_pk_bf16_f32 v21, v6, v7
	v_pk_mul_f32 v[6:7], v[74:75], v[122:123] op_sel_hi:[1,0]
	s_nop 0
	v_cvt_pk_bf16_f32 v14, v6, v7
	v_pk_mul_f32 v[6:7], v[76:77], v[122:123] op_sel_hi:[1,0]
	s_nop 0
	v_cvt_pk_bf16_f32 v15, v6, v7
	v_pk_mul_f32 v[6:7], v[78:79], v[122:123] op_sel_hi:[1,0]
	s_nop 0
	v_cvt_pk_bf16_f32 v16, v6, v7
	v_pk_mul_f32 v[6:7], v[80:81], v[122:123] op_sel_hi:[1,0]
	s_nop 0
	v_cvt_pk_bf16_f32 v17, v6, v7
	v_pk_mul_f32 v[6:7], v[98:99], v[122:123] op_sel_hi:[1,0]
	s_nop 0
	v_cvt_pk_bf16_f32 v10, v6, v7
	v_pk_mul_f32 v[6:7], v[100:101], v[122:123] op_sel_hi:[1,0]
	s_nop 0
	v_cvt_pk_bf16_f32 v11, v6, v7
	v_pk_mul_f32 v[6:7], v[102:103], v[122:123] op_sel_hi:[1,0]
	s_nop 0
	v_cvt_pk_bf16_f32 v12, v6, v7
	v_pk_mul_f32 v[6:7], v[104:105], v[122:123] op_sel_hi:[1,0]
	s_nop 0
	v_cvt_pk_bf16_f32 v13, v6, v7
	v_pk_mul_f32 v[6:7], v[106:107], v[122:123] op_sel_hi:[1,0]
	s_nop 0
	v_cvt_pk_bf16_f32 v6, v6, v7
	v_cvt_pk_bf16_f32 v7, v8, v9
	v_pk_mul_f32 v[8:9], v[118:119], v[122:123] op_sel_hi:[1,0]
	s_nop 0
	v_cvt_pk_bf16_f32 v8, v8, v9
	v_cvt_pk_bf16_f32 v9, v34, v35
	v_add_u32_e32 v70, 0x2000, v114
	v_add_u32_e32 v71, 0x4000, v114
	v_add_u32_e32 v72, 0x6000, v114
	v_add_u32_e32 v73, 0x8000, v114
	v_add_u32_e32 v74, 0xa000, v114
	v_add_u32_e32 v75, 0xc000, v114
	v_add_u32_e32 v76, 0xe000, v114
	ds_read2_b64 v[34:37], v114 offset1:4
	ds_read2_b64 v[38:41], v70 offset0:32 offset1:36
	ds_read2_b64 v[42:45], v71 offset0:64 offset1:68
	ds_read2_b64 v[46:49], v72 offset0:96 offset1:100
	ds_read2_b64 v[50:53], v73 offset0:128 offset1:132
	ds_read2_b64 v[54:57], v74 offset0:160 offset1:164
	ds_read2_b64 v[58:61], v75 offset0:192 offset1:196
	ds_read2_b64 v[62:65], v76 offset0:224 offset1:228
	s_waitcnt lgkmcnt(7)
	v_mfma_f32_16x16x32_bf16 v[34:37], v[66:69], v[34:37], 0
	s_waitcnt lgkmcnt(6)
	v_mfma_f32_16x16x32_bf16 v[38:41], v[66:69], v[38:41], 0
	s_waitcnt lgkmcnt(5)
	v_mfma_f32_16x16x32_bf16 v[42:45], v[66:69], v[42:45], 0
	s_waitcnt lgkmcnt(4)
	v_mfma_f32_16x16x32_bf16 v[46:49], v[66:69], v[46:49], 0
	s_waitcnt lgkmcnt(3)
	v_mfma_f32_16x16x32_bf16 v[50:53], v[66:69], v[50:53], 0
	s_waitcnt lgkmcnt(2)
	v_mfma_f32_16x16x32_bf16 v[54:57], v[66:69], v[54:57], 0
	s_waitcnt lgkmcnt(1)
	v_mfma_f32_16x16x32_bf16 v[58:61], v[66:69], v[58:61], 0
	s_waitcnt lgkmcnt(0)
	v_mfma_f32_16x16x32_bf16 v[62:65], v[66:69], v[62:65], 0
	ds_read2_b64 v[66:69], v114 offset0:8 offset1:12
	s_waitcnt lgkmcnt(0)
	v_mfma_f32_16x16x32_bf16 v[34:37], v[30:33], v[66:69], v[34:37]
	ds_read2_b64 v[66:69], v70 offset0:40 offset1:44
	s_waitcnt lgkmcnt(0)
	v_mfma_f32_16x16x32_bf16 v[38:41], v[30:33], v[66:69], v[38:41]
	ds_read2_b64 v[66:69], v71 offset0:72 offset1:76
	s_waitcnt lgkmcnt(0)
	v_mfma_f32_16x16x32_bf16 v[42:45], v[30:33], v[66:69], v[42:45]
	ds_read2_b64 v[66:69], v72 offset0:104 offset1:108
	s_waitcnt lgkmcnt(0)
	v_mfma_f32_16x16x32_bf16 v[46:49], v[30:33], v[66:69], v[46:49]
	ds_read2_b64 v[66:69], v73 offset0:136 offset1:140
	s_waitcnt lgkmcnt(0)
	v_mfma_f32_16x16x32_bf16 v[50:53], v[30:33], v[66:69], v[50:53]
	ds_read2_b64 v[66:69], v74 offset0:168 offset1:172
	s_waitcnt lgkmcnt(0)
	v_mfma_f32_16x16x32_bf16 v[54:57], v[30:33], v[66:69], v[54:57]
	ds_read2_b64 v[66:69], v75 offset0:200 offset1:204
	s_waitcnt lgkmcnt(0)
	v_mfma_f32_16x16x32_bf16 v[58:61], v[30:33], v[66:69], v[58:61]
	ds_read2_b64 v[66:69], v76 offset0:232 offset1:236
	s_waitcnt lgkmcnt(0)
	v_mfma_f32_16x16x32_bf16 v[30:33], v[30:33], v[66:69], v[62:65]
	s_nop 2
	ds_read2_b64 v[62:65], v114 offset0:16 offset1:20
	s_waitcnt lgkmcnt(0)
; #define LAS __attribute__((address_space(3)))
; __device__ __forceinline__ f32x4 mfma16(bf16x8 a, bf16x8 b, f32x4 c) { return __builtin_amdgcn_mfma_f32_16x16x32_bf16(a, b, c, 0, 0, 0); }
; __device__ __forceinline__ void attn_item(const P& p, const Ctx& c, int layer, int it, const bf16_t* Qp, int ldq, bf16_t* YM, int ldy, const bf16_t* Zp, int ldz) {
;     ...
; #pragma unroll
;         for (int kp = 0; kp < 8; ++kp) {
;             const bf16x8 a = pa[kp];
; #pragma unroll
;             for (int nt = 0; nt < 8; ++nt) { const LAS bf16_t* vp = Vs + (nt * 16 + l15) * 264 + 2 * kp * 16 + quad * 4;
;                 const u32x2 lo = *(const LAS u32x2*)vp, hi = *(const LAS u32x2*)(vp + 16); u32x4 bw = (u32x4){lo.x, lo.y, hi.x, hi.y}; bf16x8 bfr; __builtin_memcpy(&bfr, &bw, 16);
;                 o[nt] = mfma16(a, bfr, o[nt]); }
;             __builtin_amdgcn_sched_barrier(0);
;         }
	v_mfma_f32_16x16x32_bf16 v[34:37], v[26:29], v[62:65], v[34:37]
	ds_read2_b64 v[62:65], v70 offset0:48 offset1:52
	s_waitcnt lgkmcnt(0)
	v_mfma_f32_16x16x32_bf16 v[38:41], v[26:29], v[62:65], v[38:41]
	ds_read2_b64 v[62:65], v71 offset0:80 offset1:84
	s_waitcnt lgkmcnt(0)
	v_mfma_f32_16x16x32_bf16 v[42:45], v[26:29], v[62:65], v[42:45]
	ds_read2_b64 v[62:65], v72 offset0:112 offset1:116
	s_waitcnt lgkmcnt(0)
	v_mfma_f32_16x16x32_bf16 v[46:49], v[26:29], v[62:65], v[46:49]
	ds_read2_b64 v[62:65], v73 offset0:144 offset1:148
	s_waitcnt lgkmcnt(0)
	v_mfma_f32_16x16x32_bf16 v[50:53], v[26:29], v[62:65], v[50:53]
	ds_read2_b64 v[62:65], v74 offset0:176 offset1:180
	s_waitcnt lgkmcnt(0)
	v_mfma_f32_16x16x32_bf16 v[54:57], v[26:29], v[62:65], v[54:57]
	ds_read2_b64 v[62:65], v75 offset0:208 offset1:212
	s_waitcnt lgkmcnt(0)
	v_mfma_f32_16x16x32_bf16 v[58:61], v[26:29], v[62:65], v[58:61]
	ds_read2_b64 v[62:65], v76 offset0:240 offset1:244
	s_waitcnt lgkmcnt(0)
	v_mfma_f32_16x16x32_bf16 v[26:29], v[26:29], v[62:65], v[30:33]
	s_nop 2
	ds_read2_b64 v[30:33], v114 offset0:24 offset1:28
	s_waitcnt lgkmcnt(0)
	v_mfma_f32_16x16x32_bf16 v[30:33], v[22:25], v[30:33], v[34:37]
	s_nop 2
	ds_read2_b64 v[34:37], v70 offset0:56 offset1:60
	s_waitcnt lgkmcnt(0)
	v_mfma_f32_16x16x32_bf16 v[34:37], v[22:25], v[34:37], v[38:41]
	s_nop 2
	ds_read2_b64 v[38:41], v71 offset0:88 offset1:92
	s_waitcnt lgkmcnt(0)
	v_mfma_f32_16x16x32_bf16 v[38:41], v[22:25], v[38:41], v[42:45]
	s_nop 2
	ds_read2_b64 v[42:45], v72 offset0:120 offset1:124
	s_waitcnt lgkmcnt(0)
	v_mfma_f32_16x16x32_bf16 v[42:45], v[22:25], v[42:45], v[46:49]
	s_nop 2
	ds_read2_b64 v[46:49], v73 offset0:152 offset1:156
	s_waitcnt lgkmcnt(0)
	v_mfma_f32_16x16x32_bf16 v[46:49], v[22:25], v[46:49], v[50:53]
	s_nop 2
	ds_read2_b64 v[50:53], v74 offset0:184 offset1:188
	s_waitcnt lgkmcnt(0)
	v_mfma_f32_16x16x32_bf16 v[50:53], v[22:25], v[50:53], v[54:57]
	s_nop 2
	ds_read2_b64 v[54:57], v75 offset0:216 offset1:220
	s_waitcnt lgkmcnt(0)
	v_mfma_f32_16x16x32_bf16 v[54:57], v[22:25], v[54:57], v[58:61]
	s_nop 2
	ds_read2_b64 v[58:61], v76 offset0:248 offset1:252
	s_waitcnt lgkmcnt(0)
	v_mfma_f32_16x16x32_bf16 v[22:25], v[22:25], v[58:61], v[26:29]
	s_nop 2
	ds_read2_b64 v[26:29], v114 offset0:32 offset1:36
	v_add_u32_e32 v58, 0xe800, v114
	s_waitcnt lgkmcnt(0)
	v_mfma_f32_16x16x32_bf16 v[26:29], v[18:21], v[26:29], v[30:33]
	s_nop 2
	ds_read2_b64 v[30:33], v70 offset0:64 offset1:68
	s_waitcnt lgkmcnt(0)
	v_mfma_f32_16x16x32_bf16 v[30:33], v[18:21], v[30:33], v[34:37]
	s_nop 2
	ds_read2_b64 v[34:37], v71 offset0:96 offset1:100
	s_waitcnt lgkmcnt(0)
	v_mfma_f32_16x16x32_bf16 v[34:37], v[18:21], v[34:37], v[38:41]
	s_nop 2
	ds_read2_b64 v[38:41], v72 offset0:128 offset1:132
	s_waitcnt lgkmcnt(0)
	v_mfma_f32_16x16x32_bf16 v[38:41], v[18:21], v[38:41], v[42:45]
	s_nop 2
	ds_read2_b64 v[42:45], v73 offset0:160 offset1:164
	s_waitcnt lgkmcnt(0)
	v_mfma_f32_16x16x32_bf16 v[42:45], v[18:21], v[42:45], v[46:49]
	s_nop 2
	ds_read2_b64 v[46:49], v74 offset0:192 offset1:196
	s_waitcnt lgkmcnt(0)
	v_mfma_f32_16x16x32_bf16 v[46:49], v[18:21], v[46:49], v[50:53]
	s_nop 2
	ds_read2_b64 v[50:53], v75 offset0:224 offset1:228
	s_waitcnt lgkmcnt(0)
	v_mfma_f32_16x16x32_bf16 v[50:53], v[18:21], v[50:53], v[54:57]
	s_nop 2
	ds_read2_b64 v[54:57], v58 offset1:4
	s_waitcnt lgkmcnt(0)
	v_mfma_f32_16x16x32_bf16 v[18:21], v[18:21], v[54:57], v[22:25]
	s_nop 2
	ds_read2_b64 v[22:25], v114 offset0:40 offset1:44
	s_waitcnt lgkmcnt(0)
	v_mfma_f32_16x16x32_bf16 v[22:25], v[14:17], v[22:25], v[26:29]
	s_nop 2
	ds_read2_b64 v[26:29], v70 offset0:72 offset1:76
	s_waitcnt lgkmcnt(0)
	v_mfma_f32_16x16x32_bf16 v[26:29], v[14:17], v[26:29], v[30:33]
	s_nop 2
	ds_read2_b64 v[30:33], v71 offset0:104 offset1:108
	s_waitcnt lgkmcnt(0)
	v_mfma_f32_16x16x32_bf16 v[30:33], v[14:17], v[30:33], v[34:37]
	s_nop 2
	ds_read2_b64 v[34:37], v72 offset0:136 offset1:140
	s_waitcnt lgkmcnt(0)
	v_mfma_f32_16x16x32_bf16 v[34:37], v[14:17], v[34:37], v[38:41]
	s_nop 2
	ds_read2_b64 v[38:41], v73 offset0:168 offset1:172
	s_waitcnt lgkmcnt(0)
	v_mfma_f32_16x16x32_bf16 v[38:41], v[14:17], v[38:41], v[42:45]
	s_nop 2
	ds_read2_b64 v[42:45], v74 offset0:200 offset1:204
	s_waitcnt lgkmcnt(0)
	v_mfma_f32_16x16x32_bf16 v[42:45], v[14:17], v[42:45], v[46:49]
	s_nop 2
	ds_read2_b64 v[46:49], v75 offset0:232 offset1:236
	s_waitcnt lgkmcnt(0)
	v_mfma_f32_16x16x32_bf16 v[46:49], v[14:17], v[46:49], v[50:53]
	s_nop 2
	ds_read2_b64 v[50:53], v58 offset0:8 offset1:12
	s_waitcnt lgkmcnt(0)
	v_mfma_f32_16x16x32_bf16 v[14:17], v[14:17], v[50:53], v[18:21]
	s_nop 2
	ds_read2_b64 v[18:21], v114 offset0:48 offset1:52
	s_waitcnt lgkmcnt(0)
	v_mfma_f32_16x16x32_bf16 v[18:21], v[10:13], v[18:21], v[22:25]
	s_nop 2
	ds_read2_b64 v[22:25], v70 offset0:80 offset1:84
	s_waitcnt lgkmcnt(0)
	v_mfma_f32_16x16x32_bf16 v[22:25], v[10:13], v[22:25], v[26:29]
	s_nop 2
	ds_read2_b64 v[26:29], v71 offset0:112 offset1:116
	s_waitcnt lgkmcnt(0)
	v_mfma_f32_16x16x32_bf16 v[26:29], v[10:13], v[26:29], v[30:33]
	s_nop 2
	ds_read2_b64 v[30:33], v72 offset0:144 offset1:148
	s_waitcnt lgkmcnt(0)
	v_mfma_f32_16x16x32_bf16 v[34:37], v[10:13], v[30:33], v[34:37]
	ds_read2_b64 v[30:33], v73 offset0:176 offset1:180
	s_waitcnt lgkmcnt(0)
	v_mfma_f32_16x16x32_bf16 v[38:41], v[10:13], v[30:33], v[38:41]
	ds_read2_b64 v[30:33], v74 offset0:208 offset1:212
	s_waitcnt lgkmcnt(0)
	v_mfma_f32_16x16x32_bf16 v[42:45], v[10:13], v[30:33], v[42:45]
	ds_read2_b64 v[30:33], v75 offset0:240 offset1:244
	s_waitcnt lgkmcnt(0)
	v_mfma_f32_16x16x32_bf16 v[46:49], v[10:13], v[30:33], v[46:49]
	ds_read2_b64 v[30:33], v58 offset0:16 offset1:20
	s_waitcnt lgkmcnt(0)
; #define LAS __attribute__((address_space(3)))
; __device__ __forceinline__ bf16_t f2bf(float f) { const __bf16 r = (__bf16)f; bf16_t u; __builtin_memcpy(&u, &r, 2); return u; }
; __device__ __forceinline__ float bf2f(bf16_t b) { return __uint_as_float(((unsigned)b) << 16); }
; __device__ __forceinline__ float siluf_(float x) { return x * frcp(1.0f + __expf(-x)); }
; __device__ __forceinline__ f32x4 mfma16(bf16x8 a, bf16x8 b, f32x4 c) { return __builtin_amdgcn_mfma_f32_16x16x32_bf16(a, b, c, 0, 0, 0); }
; __device__ __forceinline__ void attn_item(const P& p, const Ctx& c, int layer, int it, const bf16_t* Qp, int ldq, bf16_t* YM, int ldy, const bf16_t* Zp, int ldz) {
;     ...
; #pragma unroll
;         for (int kp = 0; kp < 8; ++kp) {
;             const bf16x8 a = pa[kp];
; #pragma unroll
;             for (int nt = 0; nt < 8; ++nt) { const LAS bf16_t* vp = Vs + (nt * 16 + l15) * 264 + 2 * kp * 16 + quad * 4;
;                 const u32x2 lo = *(const LAS u32x2*)vp, hi = *(const LAS u32x2*)(vp + 16); u32x4 bw = (u32x4){lo.x, lo.y, hi.x, hi.y}; bf16x8 bfr; __builtin_memcpy(&bfr, &bw, 16);
;                 o[nt] = mfma16(a, bfr, o[nt]); }
;             __builtin_amdgcn_sched_barrier(0);
;         }
; #pragma unroll
;         for (int nt = 0; nt < 8; ++nt)
; #pragma unroll
;             for (int j = 0; j < 4; ++j) { const size_t rr = (size_t)(row0 + quad * 4 + j); const int cc = head * 128 + nt * 16 + l15; float ov = o[nt][j];
;                 if (Zp) ov *= siluf_(bf2f(Zp[rr * ldz + cc]));
;                 YM[rr * ldy + cc] = f2bf(ov); }
	v_mfma_f32_16x16x32_bf16 v[50:53], v[10:13], v[30:33], v[14:17]
	ds_read2_b64 v[10:13], v114 offset0:56 offset1:60
	s_waitcnt lgkmcnt(0)
	v_mfma_f32_16x16x32_bf16 v[54:57], v[6:9], v[10:13], v[18:21]
	ds_read2_b64 v[10:13], v70 offset0:88 offset1:92
	s_waitcnt lgkmcnt(0)
	v_mfma_f32_16x16x32_bf16 v[30:33], v[6:9], v[10:13], v[22:25]
	ds_read2_b64 v[10:13], v71 offset0:120 offset1:124
	s_waitcnt lgkmcnt(0)
	v_mfma_f32_16x16x32_bf16 v[26:29], v[6:9], v[10:13], v[26:29]
	ds_read2_b64 v[10:13], v72 offset0:152 offset1:156
	s_waitcnt lgkmcnt(0)
	v_mfma_f32_16x16x32_bf16 v[22:25], v[6:9], v[10:13], v[34:37]
	ds_read2_b64 v[10:13], v73 offset0:184 offset1:188
	s_nop 1
	ds_read2_b64 v[34:37], v58 offset0:24 offset1:28
	s_waitcnt lgkmcnt(1)
	v_mfma_f32_16x16x32_bf16 v[18:21], v[6:9], v[10:13], v[38:41]
	ds_read2_b64 v[10:13], v74 offset0:216 offset1:220
	s_waitcnt lgkmcnt(0)
	v_mfma_f32_16x16x32_bf16 v[14:17], v[6:9], v[10:13], v[42:45]
	ds_read2_b64 v[10:13], v75 offset0:248 offset1:252
	s_waitcnt lgkmcnt(0)
	v_mfma_f32_16x16x32_bf16 v[10:13], v[6:9], v[10:13], v[46:49]
	v_mfma_f32_16x16x32_bf16 v[6:9], v[6:9], v[34:37], v[50:53]
	v_or_b32_e32 v34, s11, v112
	v_mad_i64_i32 v[36:37], s[12:13], v34, s44, v[84:85]
	v_ashrrev_i32_e32 v35, 31, v34
	v_or_b32_e32 v48, 2, v34
	v_ashrrev_i32_e32 v49, 31, v48
	v_lshlrev_b64 v[50:51], 12, v[48:49]
	v_or_b32_e32 v52, 3, v34
	v_ashrrev_i32_e32 v53, 31, v52
	v_mov_b32_e32 v87, v5
	v_mov_b32_e32 v89, v5
	v_mov_b32_e32 v91, v5
	v_mov_b32_e32 v93, v5
	v_mov_b32_e32 v95, v5
	v_mov_b32_e32 v97, v5
	s_mov_b32 s11, 16
	s_and_b64 vcc, exec, s[6:7]
	s_mov_b64 s[6:7], 0
	s_waitcnt vmcnt(31)
	v_lshlrev_b32_e32 v36, 16, v124
	v_mul_f32_e32 v37, 0xbfb8aa3b, v36
	v_exp_f32_e32 v37, v37
	s_nop 0
	v_add_f32_e32 v37, 1.0, v37
	v_rcp_f32_e32 v37, v37
	s_nop 0
	v_mul_f32_e32 v36, v37, v36
	v_mul_f32_e32 v36, v54, v36
	v_cvt_pk_bf16_f32 v40, v36, s0
	v_lshlrev_b64 v[36:37], 12, v[34:35]
	v_lshl_add_u64 v[38:39], v[82:83], 0, v[36:37]
	global_store_short v[38:39], v40, off
	v_or_b32_e32 v38, 1, v34
	v_mad_i64_i32 v[40:41], s[12:13], v38, s44, v[84:85]
	v_ashrrev_i32_e32 v39, 31, v38
	v_lshlrev_b64 v[42:43], 12, v[38:39]
	v_lshl_add_u64 v[44:45], s[2:3], 0, v[36:37]
	s_waitcnt vmcnt(31)
	v_lshlrev_b32_e32 v35, 16, v125
	v_mul_f32_e32 v40, 0xbfb8aa3b, v35
	v_exp_f32_e32 v40, v40
	s_nop 0
	v_add_f32_e32 v40, 1.0, v40
	v_rcp_f32_e32 v40, v40
	s_nop 0
	v_mul_f32_e32 v35, v40, v35
	v_mul_f32_e32 v35, v55, v35
	v_cvt_pk_bf16_f32 v35, v35, s0
	v_lshl_add_u64 v[40:41], v[82:83], 0, v[42:43]
	global_store_short v[40:41], v35, off
	v_mad_i64_i32 v[40:41], s[12:13], v48, s44, v[84:85]
	v_lshl_add_u64 v[40:41], v[82:83], 0, v[50:51]
	v_lshlrev_b64 v[54:55], 12, v[52:53]
	v_lshl_add_u64 v[42:43], s[2:3], 0, v[42:43]
	s_waitcnt vmcnt(31)
	v_lshlrev_b32_e32 v35, 16, v126
	v_mul_f32_e32 v39, 0xbfb8aa3b, v35
	v_exp_f32_e32 v39, v39
	s_nop 0
	v_add_f32_e32 v39, 1.0, v39
	v_rcp_f32_e32 v39, v39
	s_nop 0
	v_mul_f32_e32 v35, v39, v35
	v_mul_f32_e32 v35, v56, v35
	v_cvt_pk_bf16_f32 v35, v35, s0
	global_store_short v[40:41], v35, off
	v_mad_i64_i32 v[40:41], s[12:13], v52, s44, v[84:85]
	v_lshl_add_u64 v[40:41], v[82:83], 0, v[54:55]
	s_waitcnt vmcnt(31)
	v_lshlrev_b32_e32 v35, 16, v127
	v_mul_f32_e32 v39, 0xbfb8aa3b, v35
	v_exp_f32_e32 v39, v39
	s_nop 0
	v_add_f32_e32 v39, 1.0, v39
	v_rcp_f32_e32 v39, v39
	s_nop 0
	v_mul_f32_e32 v35, v39, v35
	v_mul_f32_e32 v35, v57, v35
	v_mov_b64_e32 v[56:57], s[4:5]
	v_cvt_pk_bf16_f32 v35, v35, s0
	v_mad_i64_i32 v[46:47], s[12:13], v34, s44, v[56:57]
	global_store_short v[40:41], v35, off
	v_lshl_add_u64 v[34:35], v[46:47], 0, v[4:5]
	v_mad_i64_i32 v[40:41], s[12:13], v38, s44, v[56:57]
	v_mad_i64_i32 v[36:37], s[12:13], v48, s44, v[56:57]
	v_lshl_add_u64 v[38:39], s[2:3], 0, v[50:51]
	s_waitcnt vmcnt(31)
	v_lshlrev_b32_e32 v34, 16, v128
	v_mul_f32_e32 v35, 0xbfb8aa3b, v34
	v_exp_f32_e32 v35, v35
	s_nop 0
	v_add_f32_e32 v35, 1.0, v35
	v_rcp_f32_e32 v35, v35
	s_nop 0
	v_mul_f32_e32 v34, v35, v34
	v_mul_f32_e32 v30, v30, v34
	v_cvt_pk_bf16_f32 v30, v30, s0
	v_lshl_add_u64 v[34:35], v[44:45], 0, v[4:5]
	global_store_short v[34:35], v30, off
	v_lshl_add_u64 v[34:35], v[40:41], 0, v[4:5]
	s_waitcnt vmcnt(31)
	v_lshlrev_b32_e32 v30, 16, v129
	v_mul_f32_e32 v34, 0xbfb8aa3b, v30
	v_exp_f32_e32 v34, v34
	s_nop 0
	v_add_f32_e32 v34, 1.0, v34
	v_rcp_f32_e32 v34, v34
	s_nop 0
	v_mul_f32_e32 v30, v34, v30
	v_mul_f32_e32 v30, v31, v30
	v_cvt_pk_bf16_f32 v34, v30, s0
	v_lshl_add_u64 v[30:31], v[42:43], 0, v[4:5]
	global_store_short v[30:31], v34, off
	v_lshl_add_u64 v[30:31], v[36:37], 0, v[4:5]
	v_mad_i64_i32 v[34:35], s[12:13], v52, s44, v[56:57]
	s_waitcnt vmcnt(31)
	v_lshlrev_b32_e32 v30, 16, v130
	v_mul_f32_e32 v31, 0xbfb8aa3b, v30
	v_exp_f32_e32 v31, v31
	s_nop 0
	v_add_f32_e32 v31, 1.0, v31
	v_rcp_f32_e32 v31, v31
	s_nop 0
	v_mul_f32_e32 v30, v31, v30
	v_mul_f32_e32 v30, v32, v30
	v_cvt_pk_bf16_f32 v32, v30, s0
	v_lshl_add_u64 v[30:31], v[38:39], 0, v[4:5]
	global_store_short v[30:31], v32, off
	v_lshl_add_u64 v[30:31], v[34:35], 0, v[4:5]
	s_waitcnt vmcnt(31)
	v_lshlrev_b32_e32 v30, 16, v131
	v_mul_f32_e32 v31, 0xbfb8aa3b, v30
	v_exp_f32_e32 v31, v31
	s_nop 0
	v_add_f32_e32 v31, 1.0, v31
	v_rcp_f32_e32 v31, v31
	s_nop 0
	v_mul_f32_e32 v30, v31, v30
	v_mul_f32_e32 v30, v33, v30
	v_cvt_pk_bf16_f32 v48, v30, s0
	v_lshl_add_u64 v[30:31], s[2:3], 0, v[54:55]
	v_lshl_add_u64 v[32:33], v[30:31], 0, v[4:5]
	global_store_short v[32:33], v48, off
	v_lshl_add_u64 v[32:33], v[46:47], 0, v[86:87]
	s_waitcnt vmcnt(31)
; __device__ __forceinline__ bf16_t f2bf(float f) { const __bf16 r = (__bf16)f; bf16_t u; __builtin_memcpy(&u, &r, 2); return u; }
; __device__ __forceinline__ float bf2f(bf16_t b) { return __uint_as_float(((unsigned)b) << 16); }
; __device__ __forceinline__ float siluf_(float x) { return x * frcp(1.0f + __expf(-x)); }
; __device__ __forceinline__ void attn_item(const P& p, const Ctx& c, int layer, int it, const bf16_t* Qp, int ldq, bf16_t* YM, int ldy, const bf16_t* Zp, int ldz) {
;     ...
; #pragma unroll
;         for (int nt = 0; nt < 8; ++nt)
; #pragma unroll
;             for (int j = 0; j < 4; ++j) { const size_t rr = (size_t)(row0 + quad * 4 + j); const int cc = head * 128 + nt * 16 + l15; float ov = o[nt][j];
;                 if (Zp) ov *= siluf_(bf2f(Zp[rr * ldz + cc]));
;                 YM[rr * ldy + cc] = f2bf(ov); }
	v_lshlrev_b32_e32 v32, 16, v132
	v_mul_f32_e32 v33, 0xbfb8aa3b, v32
	v_exp_f32_e32 v33, v33
	s_nop 0
	v_add_f32_e32 v33, 1.0, v33
	v_rcp_f32_e32 v33, v33
	s_nop 0
	v_mul_f32_e32 v32, v33, v32
	v_mul_f32_e32 v26, v26, v32
	v_cvt_pk_bf16_f32 v26, v26, s0
	v_lshl_add_u64 v[32:33], v[44:45], 0, v[86:87]
	global_store_short v[32:33], v26, off
	v_lshl_add_u64 v[32:33], v[40:41], 0, v[86:87]
	s_waitcnt vmcnt(31)
	v_lshlrev_b32_e32 v26, 16, v133
	v_mul_f32_e32 v32, 0xbfb8aa3b, v26
	v_exp_f32_e32 v32, v32
	s_nop 0
	v_add_f32_e32 v32, 1.0, v32
	v_rcp_f32_e32 v32, v32
	s_nop 0
	v_mul_f32_e32 v26, v32, v26
	v_mul_f32_e32 v26, v27, v26
	v_cvt_pk_bf16_f32 v32, v26, s0
	v_lshl_add_u64 v[26:27], v[42:43], 0, v[86:87]
	global_store_short v[26:27], v32, off
	v_lshl_add_u64 v[26:27], v[36:37], 0, v[86:87]
	s_waitcnt vmcnt(31)
	v_lshlrev_b32_e32 v26, 16, v134
	v_mul_f32_e32 v27, 0xbfb8aa3b, v26
	v_exp_f32_e32 v27, v27
	s_nop 0
	v_add_f32_e32 v27, 1.0, v27
	v_rcp_f32_e32 v27, v27
	s_nop 0
	v_mul_f32_e32 v26, v27, v26
	v_mul_f32_e32 v26, v28, v26
	v_cvt_pk_bf16_f32 v28, v26, s0
	v_lshl_add_u64 v[26:27], v[38:39], 0, v[86:87]
	global_store_short v[26:27], v28, off
	v_lshl_add_u64 v[26:27], v[34:35], 0, v[86:87]
	s_waitcnt vmcnt(31)
	v_lshlrev_b32_e32 v26, 16, v135
	v_mul_f32_e32 v27, 0xbfb8aa3b, v26
	v_exp_f32_e32 v27, v27
	s_nop 0
	v_add_f32_e32 v27, 1.0, v27
	v_rcp_f32_e32 v27, v27
	s_nop 0
	v_mul_f32_e32 v26, v27, v26
	v_mul_f32_e32 v26, v29, v26
	v_cvt_pk_bf16_f32 v28, v26, s0
	v_lshl_add_u64 v[26:27], v[30:31], 0, v[86:87]
	global_store_short v[26:27], v28, off
	v_lshl_add_u64 v[26:27], v[46:47], 0, v[88:89]
	s_waitcnt vmcnt(31)
	v_lshlrev_b32_e32 v26, 16, v136
	v_mul_f32_e32 v27, 0xbfb8aa3b, v26
	v_exp_f32_e32 v27, v27
	s_nop 0
	v_add_f32_e32 v27, 1.0, v27
	v_rcp_f32_e32 v27, v27
	s_nop 0
	v_mul_f32_e32 v26, v27, v26
	v_mul_f32_e32 v22, v22, v26
	v_cvt_pk_bf16_f32 v22, v22, s0
	v_lshl_add_u64 v[26:27], v[44:45], 0, v[88:89]
	global_store_short v[26:27], v22, off
	v_lshl_add_u64 v[26:27], v[40:41], 0, v[88:89]
	s_waitcnt vmcnt(31)
	v_lshlrev_b32_e32 v22, 16, v137
	v_mul_f32_e32 v26, 0xbfb8aa3b, v22
	v_exp_f32_e32 v26, v26
	s_nop 0
	v_add_f32_e32 v26, 1.0, v26
	v_rcp_f32_e32 v26, v26
	s_nop 0
	v_mul_f32_e32 v22, v26, v22
	v_mul_f32_e32 v22, v23, v22
	v_cvt_pk_bf16_f32 v26, v22, s0
	v_lshl_add_u64 v[22:23], v[42:43], 0, v[88:89]
	global_store_short v[22:23], v26, off
	v_lshl_add_u64 v[22:23], v[36:37], 0, v[88:89]
	s_waitcnt vmcnt(31)
	v_lshlrev_b32_e32 v22, 16, v138
	v_mul_f32_e32 v23, 0xbfb8aa3b, v22
	v_exp_f32_e32 v23, v23
	s_nop 0
	v_add_f32_e32 v23, 1.0, v23
	v_rcp_f32_e32 v23, v23
	s_nop 0
	v_mul_f32_e32 v22, v23, v22
	v_mul_f32_e32 v22, v24, v22
	v_cvt_pk_bf16_f32 v24, v22, s0
	v_lshl_add_u64 v[22:23], v[38:39], 0, v[88:89]
	global_store_short v[22:23], v24, off
	v_lshl_add_u64 v[22:23], v[34:35], 0, v[88:89]
	s_waitcnt vmcnt(31)
	v_lshlrev_b32_e32 v22, 16, v139
	v_mul_f32_e32 v23, 0xbfb8aa3b, v22
	v_exp_f32_e32 v23, v23
	s_nop 0
	v_add_f32_e32 v23, 1.0, v23
	v_rcp_f32_e32 v23, v23
	s_nop 0
	v_mul_f32_e32 v22, v23, v22
	v_mul_f32_e32 v22, v25, v22
	v_cvt_pk_bf16_f32 v24, v22, s0
	v_lshl_add_u64 v[22:23], v[30:31], 0, v[88:89]
	global_store_short v[22:23], v24, off
	v_lshl_add_u64 v[22:23], v[46:47], 0, v[90:91]
	s_waitcnt vmcnt(31)
	v_lshlrev_b32_e32 v22, 16, v140
	v_mul_f32_e32 v23, 0xbfb8aa3b, v22
	v_exp_f32_e32 v23, v23
	s_nop 0
	v_add_f32_e32 v23, 1.0, v23
	v_rcp_f32_e32 v23, v23
	s_nop 0
	v_mul_f32_e32 v22, v23, v22
	v_mul_f32_e32 v18, v18, v22
	v_cvt_pk_bf16_f32 v18, v18, s0
	v_lshl_add_u64 v[22:23], v[44:45], 0, v[90:91]
	global_store_short v[22:23], v18, off
	v_lshl_add_u64 v[22:23], v[40:41], 0, v[90:91]
	s_waitcnt vmcnt(31)
	v_lshlrev_b32_e32 v18, 16, v141
	v_mul_f32_e32 v22, 0xbfb8aa3b, v18
	v_exp_f32_e32 v22, v22
	s_nop 0
	v_add_f32_e32 v22, 1.0, v22
	v_rcp_f32_e32 v22, v22
	s_nop 0
	v_mul_f32_e32 v18, v22, v18
	v_mul_f32_e32 v18, v19, v18
	v_cvt_pk_bf16_f32 v22, v18, s0
	v_lshl_add_u64 v[18:19], v[42:43], 0, v[90:91]
	global_store_short v[18:19], v22, off
	v_lshl_add_u64 v[18:19], v[36:37], 0, v[90:91]
	s_waitcnt vmcnt(31)
	v_lshlrev_b32_e32 v18, 16, v142
	v_mul_f32_e32 v19, 0xbfb8aa3b, v18
	v_exp_f32_e32 v19, v19
	s_nop 0
	v_add_f32_e32 v19, 1.0, v19
	v_rcp_f32_e32 v19, v19
	s_nop 0
	v_mul_f32_e32 v18, v19, v18
	v_mul_f32_e32 v18, v20, v18
	v_cvt_pk_bf16_f32 v20, v18, s0
	v_lshl_add_u64 v[18:19], v[38:39], 0, v[90:91]
	global_store_short v[18:19], v20, off
	v_lshl_add_u64 v[18:19], v[34:35], 0, v[90:91]
	s_waitcnt vmcnt(31)
	v_lshlrev_b32_e32 v18, 16, v143
	v_mul_f32_e32 v19, 0xbfb8aa3b, v18
	v_exp_f32_e32 v19, v19
	s_nop 0
	v_add_f32_e32 v19, 1.0, v19
	v_rcp_f32_e32 v19, v19
	s_nop 0
	v_mul_f32_e32 v18, v19, v18
	v_mul_f32_e32 v18, v21, v18
	v_cvt_pk_bf16_f32 v20, v18, s0
	v_lshl_add_u64 v[18:19], v[30:31], 0, v[90:91]
	global_store_short v[18:19], v20, off
	v_lshl_add_u64 v[18:19], v[46:47], 0, v[92:93]
	s_waitcnt vmcnt(31)
	v_lshlrev_b32_e32 v18, 16, v144
	v_mul_f32_e32 v19, 0xbfb8aa3b, v18
	v_exp_f32_e32 v19, v19
	s_nop 0
	v_add_f32_e32 v19, 1.0, v19
	v_rcp_f32_e32 v19, v19
	s_nop 0
	v_mul_f32_e32 v18, v19, v18
	v_mul_f32_e32 v14, v14, v18
	v_cvt_pk_bf16_f32 v14, v14, s0
	v_lshl_add_u64 v[18:19], v[44:45], 0, v[92:93]
	global_store_short v[18:19], v14, off
	v_lshl_add_u64 v[18:19], v[40:41], 0, v[92:93]
	s_waitcnt vmcnt(31)
	v_lshlrev_b32_e32 v14, 16, v145
	v_mul_f32_e32 v18, 0xbfb8aa3b, v14
	v_exp_f32_e32 v18, v18
	s_nop 0
	v_add_f32_e32 v18, 1.0, v18
	v_rcp_f32_e32 v18, v18
	s_nop 0
	v_mul_f32_e32 v14, v18, v14
	v_mul_f32_e32 v14, v15, v14
	v_cvt_pk_bf16_f32 v18, v14, s0
	v_lshl_add_u64 v[14:15], v[42:43], 0, v[92:93]
	global_store_short v[14:15], v18, off
	v_lshl_add_u64 v[14:15], v[36:37], 0, v[92:93]
	s_waitcnt vmcnt(31)
; __device__ __forceinline__ bf16_t f2bf(float f) { const __bf16 r = (__bf16)f; bf16_t u; __builtin_memcpy(&u, &r, 2); return u; }
; __device__ __forceinline__ float bf2f(bf16_t b) { return __uint_as_float(((unsigned)b) << 16); }
; __device__ __forceinline__ float siluf_(float x) { return x * frcp(1.0f + __expf(-x)); }
; #define PH(k) for (int _r = 0; _r < NREP(k); ++_r) if (fresh_ctx(c, p, p_arg.ws))
; #define LASTREP(k) (_r + 1 == NREP(k))
; __device__ __forceinline__ void attn_item(const P& p, const Ctx& c, int layer, int it, const bf16_t* Qp, int ldq, bf16_t* YM, int ldy, const bf16_t* Zp, int ldz) {
;     ...
; #pragma unroll
;         for (int nt = 0; nt < 8; ++nt)
; #pragma unroll
;             for (int j = 0; j < 4; ++j) { const size_t rr = (size_t)(row0 + quad * 4 + j); const int cc = head * 128 + nt * 16 + l15; float ov = o[nt][j];
;                 if (Zp) ov *= siluf_(bf2f(Zp[rr * ldz + cc]));
;                 YM[rr * ldy + cc] = f2bf(ov); }
; __global__ __launch_bounds__(512) void fwd_megakernel(P p_arg) {
;     ...
;         for (int it = c.bid; it < 256; it += c.G) {
;             if (it < 192) { PH(11) rwkv_chunk_item(p, c, seg, it, LASTREP(11)); }
;             else { PH(5) attn_item(p, c, 1, it - 192, (const bf16_t*)(c.seg + S1_P2), P2W, (bf16_t*)(c.seg + S1_Y) + DMIX, DIN, (const bf16_t*)(c.seg + S1_P2) + 512 + DMIX, P2W);
;                    if (c.G == 256) { PH(1) if (seg + 1 < NSEG) phase_apre(p, c, seg + 1, it - 192, 64); } }
	v_lshlrev_b32_e32 v14, 16, v146
	v_mul_f32_e32 v15, 0xbfb8aa3b, v14
	v_exp_f32_e32 v15, v15
	s_nop 0
	v_add_f32_e32 v15, 1.0, v15
	v_rcp_f32_e32 v15, v15
	s_nop 0
	v_mul_f32_e32 v14, v15, v14
	v_mul_f32_e32 v14, v16, v14
	v_cvt_pk_bf16_f32 v16, v14, s0
	v_lshl_add_u64 v[14:15], v[38:39], 0, v[92:93]
	global_store_short v[14:15], v16, off
	v_lshl_add_u64 v[14:15], v[34:35], 0, v[92:93]
	s_waitcnt vmcnt(31)
	v_lshlrev_b32_e32 v14, 16, v147
	v_mul_f32_e32 v15, 0xbfb8aa3b, v14
	v_exp_f32_e32 v15, v15
	s_nop 0
	v_add_f32_e32 v15, 1.0, v15
	v_rcp_f32_e32 v15, v15
	s_nop 0
	v_mul_f32_e32 v14, v15, v14
	v_mul_f32_e32 v14, v17, v14
	v_cvt_pk_bf16_f32 v16, v14, s0
	v_lshl_add_u64 v[14:15], v[30:31], 0, v[92:93]
	global_store_short v[14:15], v16, off
	v_lshl_add_u64 v[14:15], v[46:47], 0, v[94:95]
	s_waitcnt vmcnt(31)
	v_lshlrev_b32_e32 v14, 16, v148
	v_mul_f32_e32 v15, 0xbfb8aa3b, v14
	v_exp_f32_e32 v15, v15
	s_nop 0
	v_add_f32_e32 v15, 1.0, v15
	v_rcp_f32_e32 v15, v15
	s_nop 0
	v_mul_f32_e32 v14, v15, v14
	v_mul_f32_e32 v10, v10, v14
	v_cvt_pk_bf16_f32 v10, v10, s0
	v_lshl_add_u64 v[14:15], v[44:45], 0, v[94:95]
	global_store_short v[14:15], v10, off
	v_lshl_add_u64 v[14:15], v[40:41], 0, v[94:95]
	s_waitcnt vmcnt(31)
	v_lshlrev_b32_e32 v10, 16, v149
	v_mul_f32_e32 v14, 0xbfb8aa3b, v10
	v_exp_f32_e32 v14, v14
	s_nop 0
	v_add_f32_e32 v14, 1.0, v14
	v_rcp_f32_e32 v14, v14
	s_nop 0
	v_mul_f32_e32 v10, v14, v10
	v_mul_f32_e32 v10, v11, v10
	v_cvt_pk_bf16_f32 v14, v10, s0
	v_lshl_add_u64 v[10:11], v[42:43], 0, v[94:95]
	global_store_short v[10:11], v14, off
	v_lshl_add_u64 v[10:11], v[36:37], 0, v[94:95]
	s_waitcnt vmcnt(31)
	v_lshlrev_b32_e32 v10, 16, v150
	v_mul_f32_e32 v11, 0xbfb8aa3b, v10
	v_exp_f32_e32 v11, v11
	s_nop 0
	v_add_f32_e32 v11, 1.0, v11
	v_rcp_f32_e32 v11, v11
	s_nop 0
	v_mul_f32_e32 v10, v11, v10
	v_mul_f32_e32 v10, v12, v10
	v_cvt_pk_bf16_f32 v12, v10, s0
	v_lshl_add_u64 v[10:11], v[38:39], 0, v[94:95]
	global_store_short v[10:11], v12, off
	v_lshl_add_u64 v[10:11], v[34:35], 0, v[94:95]
	s_waitcnt vmcnt(31)
	v_lshlrev_b32_e32 v10, 16, v151
	v_mul_f32_e32 v11, 0xbfb8aa3b, v10
	v_exp_f32_e32 v11, v11
	s_nop 0
	v_add_f32_e32 v11, 1.0, v11
	v_rcp_f32_e32 v11, v11
	s_nop 0
	v_mul_f32_e32 v10, v11, v10
	v_mul_f32_e32 v10, v13, v10
	v_cvt_pk_bf16_f32 v12, v10, s0
	v_lshl_add_u64 v[10:11], v[30:31], 0, v[94:95]
	global_store_short v[10:11], v12, off
	v_lshl_add_u64 v[10:11], v[46:47], 0, v[96:97]
	s_waitcnt vmcnt(31)
	v_lshlrev_b32_e32 v10, 16, v152
	v_mul_f32_e32 v11, 0xbfb8aa3b, v10
	v_exp_f32_e32 v11, v11
	s_nop 0
	v_add_f32_e32 v11, 1.0, v11
	v_rcp_f32_e32 v11, v11
	s_nop 0
	v_mul_f32_e32 v10, v11, v10
	v_mul_f32_e32 v6, v6, v10
	v_cvt_pk_bf16_f32 v6, v6, s0
	v_lshl_add_u64 v[10:11], v[44:45], 0, v[96:97]
	global_store_short v[10:11], v6, off
	v_lshl_add_u64 v[10:11], v[40:41], 0, v[96:97]
	s_waitcnt vmcnt(31)
	v_lshlrev_b32_e32 v6, 16, v153
	v_mul_f32_e32 v10, 0xbfb8aa3b, v6
	v_exp_f32_e32 v10, v10
	s_nop 0
	v_add_f32_e32 v10, 1.0, v10
	v_rcp_f32_e32 v10, v10
	s_nop 0
	v_mul_f32_e32 v6, v10, v6
	v_mul_f32_e32 v6, v7, v6
	v_cvt_pk_bf16_f32 v10, v6, s0
	v_lshl_add_u64 v[6:7], v[42:43], 0, v[96:97]
	global_store_short v[6:7], v10, off
	v_lshl_add_u64 v[6:7], v[36:37], 0, v[96:97]
	s_waitcnt vmcnt(31)
	v_lshlrev_b32_e32 v6, 16, v154
	v_mul_f32_e32 v7, 0xbfb8aa3b, v6
	v_exp_f32_e32 v7, v7
	s_nop 0
	v_add_f32_e32 v7, 1.0, v7
	v_rcp_f32_e32 v7, v7
	s_nop 0
	v_mul_f32_e32 v6, v7, v6
	v_mul_f32_e32 v6, v8, v6
	v_cvt_pk_bf16_f32 v8, v6, s0
	v_lshl_add_u64 v[6:7], v[38:39], 0, v[96:97]
	global_store_short v[6:7], v8, off
	v_lshl_add_u64 v[6:7], v[34:35], 0, v[96:97]
	s_waitcnt vmcnt(31)
	v_lshlrev_b32_e32 v6, 16, v155
	v_mul_f32_e32 v7, 0xbfb8aa3b, v6
	v_exp_f32_e32 v7, v7
	s_nop 0
	v_add_f32_e32 v7, 1.0, v7
	v_rcp_f32_e32 v7, v7
	s_nop 0
	v_mul_f32_e32 v6, v7, v6
	v_mul_f32_e32 v6, v9, v6
	v_cvt_pk_bf16_f32 v8, v6, s0
	v_lshl_add_u64 v[6:7], v[30:31], 0, v[96:97]
	global_store_short v[6:7], v8, off
	s_cbranch_vccnz .LBB0_826
	s_cmpk_eq_i32 s23, 0x100
	s_cbranch_scc0 .LBB0_832
	v_mov_b32_e32 v6, v217
	s_mov_b32 s23, s34
	s_mov_b32 s2, s90
	s_mov_b64 s[6:7], s[92:93]
	v_readfirstlane_b32 s4, v6
	s_mov_b64 s[2:3], 0
	s_and_b64 vcc, exec, s[8:9]
	s_cbranch_vccz .LBB0_832
	s_lshl_b32 s5, s22, 3
	s_ashr_i32 s4, s4, 6
	s_add_i32 s5, s5, s4
	s_add_i32 s4, s5, 0xfffffa00
	s_cmpk_gt_i32 s4, 0xfff
	s_cbranch_scc1 .LBB0_832
	v_xor_b32_e32 v2, 8, v212
	v_cmp_lt_i32_e32 vcc, v2, v111
	s_load_dwordx2 s[10:11], s[6:7], 0x0
	s_nop 0
	s_load_dwordx2 s[6:7], s[6:7], 0x10
	v_cndmask_b32_e32 v2, v212, v2, vcc
	v_lshlrev_b32_e32 v26, 2, v2
	v_xor_b32_e32 v2, 4, v212
	v_cmp_lt_i32_e32 vcc, v2, v111
	s_nop 1
	v_cndmask_b32_e32 v2, v212, v2, vcc
	v_lshlrev_b32_e32 v27, 2, v2
	v_xor_b32_e32 v2, 2, v212
	v_cmp_lt_i32_e32 vcc, v2, v111
	s_nop 1
	v_cndmask_b32_e32 v2, v212, v2, vcc
	v_lshlrev_b32_e32 v28, 2, v2
	v_xor_b32_e32 v2, 1, v212
	v_cmp_lt_i32_e32 vcc, v2, v111
	s_nop 1
	v_cndmask_b32_e32 v2, v212, v2, vcc
	v_lshlrev_b32_e32 v29, 2, v2
	v_lshlrev_b32_e32 v2, 4, v6
	v_and_b32_e32 v4, 0x3f0, v2
	s_waitcnt lgkmcnt(0)
	v_lshl_add_u64 v[22:23], s[6:7], 0, v[4:5]
	s_add_i32 s6, s5, 0xfffff800
	s_ashr_i32 s5, s4, 31
	s_lshl_b64 s[4:5], s[4:5], 11
	s_add_u32 s2, s2, s4
	s_addc_u32 s3, s3, s5
	v_readlane_b32 s4, v255, 15
	v_lshl_add_u64 v[2:3], s[10:11], 0, v[4:5]
	v_and_b32_e32 v4, 63, v6
	s_add_u32 s2, s4, s2
	v_readlane_b32 s4, v255, 16
	v_lshlrev_b32_e32 v4, 3, v4
	s_addc_u32 s3, s4, s3
	v_lshl_add_u64 v[24:25], s[2:3], 0, v[4:5]
